# speedup vs baseline: 1.0077x; 1.0077x over previous
; #define otid() (W * 64 + olane())
; __device__ __forceinline__ void dil_wave_item(const bf16* __restrict__ qkv, bf16* __restrict__ odil, float* __restrict__ lse,
;                               int pat, int g  , int head, char* wl  , const int W) {
;   const int lane = otid() & 63, r32 = lane & 31, hi = lane >> 5;
;   const int dil = (pat == 0) ? 1 : (pat == 1 ? 4 : 16);
;   int seq0, slen, gl;
;   if (g < 256) { seq0 = 0; slen = 8192; gl = g; } else if (g < 512) { seq0 = 8192; slen = 8192; gl = g - 256; } else { seq0 = 16384; slen = 16384; gl = g - 512; }
;   const int L = slen / dil, tpr = L / 32, res = gl / tpr, i0 = (gl % tpr) * 32;
;   const int tbase = seq0 + res;
;   bf16x8 qr[4];
;   { const bf16* qp = qkv + (size_t)(tbase + (i0 + r32) * dil) * LDQ + 1536 + head * 64 + hi * 8;
; #pragma unroll
;     for (int d0 = 0; d0 < 4; ++d0) qr[d0] = *reinterpret_cast<const bf16x8*>(qp + d0 * 16); }
;   f32x16 sc[5];
; #pragma unroll
;   for (int kb = 0; kb < 5; ++kb) {
;     int kc = i0 - 64 + kb * 32 + r32; kc = min(max(kc, 0), L - 1);
;     const bf16* kp = qkv + (size_t)(tbase + kc * dil) * LDQ + 2048 + head * 64 + hi * 8;
;     f32x16 a = {};
; #pragma unroll
;     for (int d0 = 0; d0 < 4; ++d0) {
;       bf16x8 kf = *reinterpret_cast<const bf16x8*>(kp + d0 * 16);
;       a = __builtin_amdgcn_mfma_f32_32x32x16_bf16(kf, qr[d0], a, 0, 0, 0);
;     }
;     sc[kb] = a;
;   }
.LBB0_90:
	s_add_i32 s7, s70, 0x3ff
	s_and_b32 s11, s70, 0xfffffc00
	s_cmpk_eq_i32 s11, 0x400
	s_cselect_b32 s11, 2, 4
	s_cmpk_gt_u32 s7, 0x7fe
	s_cselect_b32 s71, s11, 0
	s_lshr_b32 s7, s5, s71
	s_lshr_b32 s5, s7, 5
	s_sext_i32_i16 s11, s5
	v_cvt_f32_i32_e32 v0, s11
	s_sext_i32_i16 s66, s6
	v_cvt_f32_i32_e32 v1, s66
	s_xor_b32 s11, s66, s11
	v_rcp_iflag_f32_e32 v2, v0
	s_ashr_i32 s11, s11, 30
	s_or_b32 s11, s11, 1
	v_and_b32_e32 v91, 31, v92
	v_mul_f32_e32 v2, v1, v2
	v_trunc_f32_e32 v2, v2
	v_fma_f32 v1, -v2, v0, v1
	v_cvt_i32_f32_e32 v2, v2
	v_cmp_ge_f32_e64 s[66:67], |v1|, |v0|
	s_and_b64 s[66:67], s[66:67], exec
	s_cselect_b32 s11, s11, 0
	v_readfirstlane_b32 s66, v2
	s_add_i32 s11, s66, s11
	s_sext_i32_i16 s66, s11
	s_mul_i32 s11, s11, s5
	s_sub_i32 s5, s6, s11
	s_sext_i32_i16 s5, s5
	s_lshl_b32 s78, s5, 5
	v_or_b32_e32 v134, s78, v91
	v_subrev_u32_e32 v87, 64, v134
	s_add_i32 s6, s7, -1
	v_max_i32_e32 v4, 0, v87
	v_min_u32_e32 v4, s6, v4
	s_add_i32 s79, s4, s66
	v_lshlrev_b32_e32 v4, s71, v4
	v_add_u32_e32 v4, s79, v4
	v_bfe_u32 v90, v92, 5, 1
	v_mad_i64_i32 v[4:5], s[4:5], v4, s62, v[84:85]
	v_lshlrev_b32_e32 v82, 4, v90
	v_lshl_add_u64 v[4:5], v[4:5], 0, s[74:75]
	v_lshl_add_u64 v[20:21], v[4:5], 0, v[82:83]
	v_max_i32_e32 v8, 0xffffffe0, v87
	v_add_co_u32_e32 v4, vcc, s63, v20
	v_add_u32_e32 v8, 32, v8
	s_nop 0
	v_addc_co_u32_e32 v5, vcc, 0, v21, vcc
	v_min_u32_e32 v8, s6, v8
	v_lshlrev_b32_e32 v86, s71, v134
	global_load_dwordx4 v[4:7], v[4:5], off
	v_lshlrev_b32_e32 v8, s71, v8
	v_add_u32_e32 v0, s79, v86
	v_add_u32_e32 v8, s79, v8
	v_mad_i64_i32 v[0:1], s[4:5], v0, s62, v[80:81]
	v_mad_i64_i32 v[8:9], s[4:5], v8, s62, v[84:85]
	v_lshl_add_u64 v[126:127], v[0:1], 0, v[82:83]
	v_lshl_add_u64 v[8:9], v[8:9], 0, s[74:75]
	global_load_dwordx4 v[0:3], v[126:127], off offset:3072
	v_lshl_add_u64 v[22:23], v[8:9], 0, v[82:83]
	v_add_co_u32_e32 v8, vcc, s63, v22
	v_max_i32_e32 v12, 0xffffffc0, v87
	s_nop 0
	v_addc_co_u32_e32 v9, vcc, 0, v23, vcc
	global_load_dwordx4 v[8:11], v[8:9], off
	v_add_u32_e32 v12, 64, v12
	v_min_u32_e32 v12, s6, v12
	s_waitcnt vmcnt(11)
	v_max_i32_e32 v16, 0xffffffa0, v87
	v_lshlrev_b32_e32 v12, s71, v12
	v_add_u32_e32 v16, 0x60, v16
	v_add_u32_e32 v12, s79, v12
	v_min_u32_e32 v16, s6, v16
	v_mad_i64_i32 v[12:13], s[4:5], v12, s62, v[84:85]
	v_lshlrev_b32_e32 v16, s71, v16
	v_lshl_add_u64 v[12:13], v[12:13], 0, s[74:75]
	v_add_u32_e32 v16, s79, v16
	v_lshl_add_u64 v[24:25], v[12:13], 0, v[82:83]
	v_mad_i64_i32 v[16:17], s[4:5], v16, s62, v[84:85]
	v_add_co_u32_e32 v12, vcc, s63, v24
	v_lshl_add_u64 v[16:17], v[16:17], 0, s[74:75]
	s_nop 0
	v_addc_co_u32_e32 v13, vcc, 0, v25, vcc
	v_lshl_add_u64 v[26:27], v[16:17], 0, v[82:83]
	v_add_co_u32_e32 v16, vcc, s63, v26
	global_load_dwordx4 v[12:15], v[12:13], off
	s_nop 0
	v_addc_co_u32_e32 v17, vcc, 0, v27, vcc
	v_lshl_add_u64 v[118:119], v[20:21], 0, s[8:9]
	v_lshl_add_u64 v[128:129], v[22:23], 0, s[8:9]
	global_load_dwordx4 v[16:19], v[16:17], off
	s_nop 0
	global_load_dwordx4 v[94:97], v[118:119], off offset:32
	global_load_dwordx4 v[98:101], v[126:127], off offset:3104
	global_load_dwordx4 v[102:105], v[118:119], off offset:96
	v_lshl_add_u64 v[130:131], v[24:25], 0, s[8:9]
	v_lshl_add_u64 v[132:133], v[26:27], 0, s[8:9]
	v_lshlrev_b32_e32 v90, 2, v90
	v_sub_u32_e32 v93, v90, v91
	s_waitcnt vmcnt(6)
	v_mfma_f32_32x32x16_bf16 v[64:79], v[4:7], v[0:3], 0
	global_load_dwordx4 v[4:7], v[128:129], off offset:32
	global_load_dwordx4 v[106:109], v[128:129], off offset:96
	global_load_dwordx4 v[110:113], v[130:131], off offset:96
	s_waitcnt vmcnt(8)
	v_mfma_f32_32x32x16_bf16 v[48:63], v[8:11], v[0:3], 0
	global_load_dwordx4 v[8:11], v[130:131], off offset:32
	s_waitcnt vmcnt(8)
	v_mfma_f32_32x32x16_bf16 v[32:47], v[12:15], v[0:3], 0
	global_load_dwordx4 v[12:15], v[132:133], off offset:32
	global_load_dwordx4 v[114:117], v[132:133], off offset:96
	s_nop 0
	global_load_dwordx4 v[118:121], v[118:119], off offset:64
	s_nop 0
	global_load_dwordx4 v[122:125], v[126:127], off offset:3136
	s_waitcnt vmcnt(9)
	v_mfma_f32_32x32x16_bf16 v[64:79], v[94:97], v[98:101], v[64:79]
	global_load_dwordx4 v[94:97], v[128:129], off offset:64
	v_mfma_f32_32x32x16_bf16 v[16:31], v[16:19], v[0:3], 0
	s_waitcnt vmcnt(4)
	v_mfma_f32_32x32x16_bf16 v[16:31], v[12:15], v[98:101], v[16:31]
	v_mfma_f32_32x32x16_bf16 v[48:63], v[4:7], v[98:101], v[48:63]
	global_load_dwordx4 v[4:7], v[130:131], off offset:64
	s_nop 0
	global_load_dwordx4 v[126:129], v[126:127], off offset:3168
	v_mfma_f32_32x32x16_bf16 v[32:47], v[8:11], v[98:101], v[32:47]
	global_load_dwordx4 v[8:11], v[132:133], off offset:64
	s_waitcnt vmcnt(3)
	v_mfma_f32_32x32x16_bf16 v[48:63], v[94:97], v[122:125], v[48:63]
	s_waitcnt vmcnt(2)
	v_mfma_f32_32x32x16_bf16 v[32:47], v[4:7], v[122:125], v[32:47]
	v_max_i32_e32 v4, 0xffffff80, v87
	v_add_u32_e32 v4, 0x80, v4
	v_min_u32_e32 v4, s6, v4
	v_lshlrev_b32_e32 v4, s71, v4
	v_add_u32_e32 v4, s79, v4
	v_mad_i64_i32 v[4:5], s[4:5], v4, s62, v[84:85]
	v_lshl_add_u64 v[4:5], v[4:5], 0, s[74:75]
	s_waitcnt vmcnt(0)
	v_mfma_f32_32x32x16_bf16 v[16:31], v[8:11], v[122:125], v[16:31]
	v_lshl_add_u64 v[8:9], v[4:5], 0, v[82:83]
	v_add_co_u32_e32 v4, vcc, s63, v8
	v_and_b32_e32 v87, 63, v92
	s_nop 0
	v_addc_co_u32_e32 v5, vcc, 0, v9, vcc
	global_load_dwordx4 v[4:7], v[4:5], off
	v_mfma_f32_32x32x16_bf16 v[64:79], v[118:121], v[122:125], v[64:79]
	v_cmp_gt_u32_e32 vcc, s64, v93
	v_mfma_f32_32x32x16_bf16 v[48:63], v[106:109], v[126:129], v[48:63]
	v_lshl_add_u64 v[106:107], v[8:9], 0, s[8:9]
	v_mfma_f32_32x32x16_bf16 v[64:79], v[102:105], v[126:129], v[64:79]
	global_load_dwordx4 v[94:97], v[106:107], off offset:32
	global_load_dwordx4 v[102:105], v[106:107], off offset:96
	s_nop 7
	v_mul_f32_e32 v48, 0x3e38aa3b, v48
	global_load_dwordx4 v[106:109], v[106:107], off offset:64
	v_mul_f32_e32 v49, 0x3e38aa3b, v49
	v_mul_f32_e32 v50, 0x3e38aa3b, v50
	v_mul_f32_e32 v51, 0x3e38aa3b, v51
	v_mul_f32_e32 v52, 0x3e38aa3b, v52
	s_waitcnt vmcnt(3)
; __device__ __forceinline__ void dil_wave_item(const bf16* __restrict__ qkv, bf16* __restrict__ odil, float* __restrict__ lse,
;                               int pat, int g  , int head, char* wl  , const int W) {
;     ...
;   for (int kb = 0; kb < 5; ++kb) {
;     int kc = i0 - 64 + kb * 32 + r32; kc = min(max(kc, 0), L - 1);
;     const bf16* kp = qkv + (size_t)(tbase + kc * dil) * LDQ + 2048 + head * 64 + hi * 8;
;     f32x16 a = {};
; #pragma unroll
;     for (int d0 = 0; d0 < 4; ++d0) {
;       bf16x8 kf = *reinterpret_cast<const bf16x8*>(kp + d0 * 16);
;       a = __builtin_amdgcn_mfma_f32_32x32x16_bf16(kf, qr[d0], a, 0, 0, 0);
;     }
;     sc[kb] = a;
;   }
;     ...
;   for (int kb = 0; kb < 5; ++kb) {
;     bf16x8 vr[4];
; #pragma unroll
;     for (int i = 0; i < 4; ++i) {
;       const int key = i * 8 + (lane >> 3);
;       int kc = i0 - 64 + kb * 32 + key; kc = min(max(kc, 0), L - 1);
;       vr[i] = *reinterpret_cast<const bf16x8*>(qkv + (size_t)(tbase + kc * dil) * LDQ + 2560 + head * 64 + (lane & 7) * 8);
	v_mfma_f32_32x32x16_bf16 v[0:15], v[4:7], v[0:3], 0
	v_mul_f32_e32 v64, 0x3e38aa3b, v64
	v_mul_f32_e32 v65, 0x3e38aa3b, v65
	v_mul_f32_e32 v66, 0x3e38aa3b, v66
	v_mul_f32_e32 v67, 0x3e38aa3b, v67
	v_mul_f32_e32 v68, 0x3e38aa3b, v68
	v_mul_f32_e32 v69, 0x3e38aa3b, v69
	v_mul_f32_e32 v70, 0x3e38aa3b, v70
	s_waitcnt vmcnt(2)
	v_mfma_f32_32x32x16_bf16 v[0:15], v[94:97], v[98:101], v[0:15]
	v_add_u32_e32 v94, v134, v93
	v_subrev_u32_e32 v95, 64, v94
	v_cmp_gt_u32_e64 s[4:5], s7, v95
	s_and_b64 vcc, vcc, s[4:5]
	v_subrev_u32_e32 v95, 63, v94
	v_add_u32_e32 v96, 1, v93
	v_cndmask_b32_e32 v64, v89, v64, vcc
	v_cmp_gt_u32_e32 vcc, s64, v96
	v_cmp_gt_u32_e64 s[4:5], s7, v95
	s_waitcnt vmcnt(0)
	v_mfma_f32_32x32x16_bf16 v[0:15], v[106:109], v[122:125], v[0:15]
	v_bfe_u32 v232, v92, 3, 3
	v_and_b32_e32 v233, 7, v92
	v_add_u32_e32 v232, s78, v232
	v_lshlrev_b32_e32 v233, 4, v233
	v_add_u32_e32 v233, s74, v233
	v_add_u32_e32 v233, 0x1400, v233
	v_add_u32_e32 v234, 0xffffffc0, v232
	v_max_i32_e32 v234, 0, v234
	v_min_u32_e32 v234, s6, v234
	v_lshlrev_b32_e32 v234, s71, v234
	v_add_u32_e32 v234, s79, v234
	v_mad_u32_u24 v234, v234, s62, v233
	global_load_dwordx4 v[152:155], v234, s[36:37]
	v_add_u32_e32 v235, 0xffffffc8, v232
	v_max_i32_e32 v235, 0, v235
	v_min_u32_e32 v235, s6, v235
	v_lshlrev_b32_e32 v235, s71, v235
	v_add_u32_e32 v235, s79, v235
	v_mad_u32_u24 v235, v235, s62, v233
	global_load_dwordx4 v[156:159], v235, s[36:37]
	v_add_u32_e32 v234, 0xffffffd0, v232
	v_max_i32_e32 v234, 0, v234
	v_min_u32_e32 v234, s6, v234
	v_lshlrev_b32_e32 v234, s71, v234
	v_add_u32_e32 v234, s79, v234
	v_mad_u32_u24 v234, v234, s62, v233
	global_load_dwordx4 v[160:163], v234, s[36:37]
	v_add_u32_e32 v235, 0xffffffd8, v232
	v_max_i32_e32 v235, 0, v235
	v_min_u32_e32 v235, s6, v235
	v_lshlrev_b32_e32 v235, s71, v235
	v_add_u32_e32 v235, s79, v235
	v_mad_u32_u24 v235, v235, s62, v233
	global_load_dwordx4 v[164:167], v235, s[36:37]
	v_add_u32_e32 v234, 0xffffffe0, v232
	v_max_i32_e32 v234, 0, v234
	v_min_u32_e32 v234, s6, v234
	v_lshlrev_b32_e32 v234, s71, v234
	v_add_u32_e32 v234, s79, v234
	v_mad_u32_u24 v234, v234, s62, v233
	global_load_dwordx4 v[168:171], v234, s[36:37]
	v_add_u32_e32 v235, 0xffffffe8, v232
	v_max_i32_e32 v235, 0, v235
	v_min_u32_e32 v235, s6, v235
	v_lshlrev_b32_e32 v235, s71, v235
	v_add_u32_e32 v235, s79, v235
	v_mad_u32_u24 v235, v235, s62, v233
	global_load_dwordx4 v[172:175], v235, s[36:37]
	v_add_u32_e32 v234, -16, v232
	v_max_i32_e32 v234, 0, v234
	v_min_u32_e32 v234, s6, v234
	v_lshlrev_b32_e32 v234, s71, v234
	v_add_u32_e32 v234, s79, v234
	v_mad_u32_u24 v234, v234, s62, v233
	global_load_dwordx4 v[176:179], v234, s[36:37]
	v_add_u32_e32 v235, -8, v232
	v_max_i32_e32 v235, 0, v235
	v_min_u32_e32 v235, s6, v235
	v_lshlrev_b32_e32 v235, s71, v235
	v_add_u32_e32 v235, s79, v235
	v_mad_u32_u24 v235, v235, s62, v233
	global_load_dwordx4 v[180:183], v235, s[36:37]
	v_add_u32_e32 v234, 0, v232
	v_max_i32_e32 v234, 0, v234
	v_min_u32_e32 v234, s6, v234
	v_lshlrev_b32_e32 v234, s71, v234
	v_add_u32_e32 v234, s79, v234
	v_mad_u32_u24 v234, v234, s62, v233
	global_load_dwordx4 v[184:187], v234, s[36:37]
	v_add_u32_e32 v235, 8, v232
	v_max_i32_e32 v235, 0, v235
	v_min_u32_e32 v235, s6, v235
	v_lshlrev_b32_e32 v235, s71, v235
	v_add_u32_e32 v235, s79, v235
	v_mad_u32_u24 v235, v235, s62, v233
	global_load_dwordx4 v[188:191], v235, s[36:37]
	v_add_u32_e32 v234, 16, v232
	v_max_i32_e32 v234, 0, v234
	v_min_u32_e32 v234, s6, v234
	v_lshlrev_b32_e32 v234, s71, v234
	v_add_u32_e32 v234, s79, v234
	v_mad_u32_u24 v234, v234, s62, v233
	global_load_dwordx4 v[192:195], v234, s[36:37]
	v_add_u32_e32 v235, 24, v232
	v_max_i32_e32 v235, 0, v235
	v_min_u32_e32 v235, s6, v235
	v_lshlrev_b32_e32 v235, s71, v235
	v_add_u32_e32 v235, s79, v235
	v_mad_u32_u24 v235, v235, s62, v233
	global_load_dwordx4 v[196:199], v235, s[36:37]
	v_add_u32_e32 v234, 32, v232
	v_max_i32_e32 v234, 0, v234
	v_min_u32_e32 v234, s6, v234
	v_lshlrev_b32_e32 v234, s71, v234
	v_add_u32_e32 v234, s79, v234
	v_mad_u32_u24 v234, v234, s62, v233
	global_load_dwordx4 v[200:203], v234, s[36:37]
	v_add_u32_e32 v235, 40, v232
	v_max_i32_e32 v235, 0, v235
	v_min_u32_e32 v235, s6, v235
	v_lshlrev_b32_e32 v235, s71, v235
	v_add_u32_e32 v235, s79, v235
	v_mad_u32_u24 v235, v235, s62, v233
	global_load_dwordx4 v[204:207], v235, s[36:37]
	v_add_u32_e32 v234, 48, v232
	v_max_i32_e32 v234, 0, v234
	v_min_u32_e32 v234, s6, v234
	v_lshlrev_b32_e32 v234, s71, v234
	v_add_u32_e32 v234, s79, v234
	v_mad_u32_u24 v234, v234, s62, v233
	global_load_dwordx4 v[208:211], v234, s[36:37]
	v_add_u32_e32 v235, 56, v232
	v_max_i32_e32 v235, 0, v235
	v_min_u32_e32 v235, s6, v235
	v_lshlrev_b32_e32 v235, s71, v235
	v_add_u32_e32 v235, s79, v235
	v_mad_u32_u24 v235, v235, s62, v233
	global_load_dwordx4 v[212:215], v235, s[36:37]
	v_add_u32_e32 v234, 64, v232
	v_max_i32_e32 v234, 0, v234
	v_min_u32_e32 v234, s6, v234
	v_lshlrev_b32_e32 v234, s71, v234
	v_add_u32_e32 v234, s79, v234
	v_mad_u32_u24 v234, v234, s62, v233
	global_load_dwordx4 v[216:219], v234, s[36:37]
	v_add_u32_e32 v235, 0x00000048, v232
	v_max_i32_e32 v235, 0, v235
	v_min_u32_e32 v235, s6, v235
	v_lshlrev_b32_e32 v235, s71, v235
	v_add_u32_e32 v235, s79, v235
	v_mad_u32_u24 v235, v235, s62, v233
	global_load_dwordx4 v[220:223], v235, s[36:37]
	v_add_u32_e32 v234, 0x00000050, v232
	v_max_i32_e32 v234, 0, v234
	v_min_u32_e32 v234, s6, v234
	v_lshlrev_b32_e32 v234, s71, v234
	v_add_u32_e32 v234, s79, v234
	v_mad_u32_u24 v234, v234, s62, v233
	global_load_dwordx4 v[224:227], v234, s[36:37]
	v_add_u32_e32 v235, 0x00000058, v232
	v_max_i32_e32 v235, 0, v235
; __device__ __forceinline__ int crow(int r, int hi) { return (r & 3) + 8 * (r >> 2) + 4 * hi; }
; __device__ __forceinline__ void dil_wave_item(const bf16* __restrict__ qkv, bf16* __restrict__ odil, float* __restrict__ lse,
;                               int pat, int g  , int head, char* wl  , const int W) {
;     ...
;   float mx = -1e30f;
; #pragma unroll
;   for (int kb = 0; kb < 5; ++kb)
; #pragma unroll
;     for (int r = 0; r < 16; ++r) {
;       const int rel = kb * 32 - 64 + crow(r, hi) - r32;
;       const int kc = i0 + r32 + rel;
;       const bool ok = (rel >= -64) && (rel <= 64) && (kc >= 0) && (kc < L);
;       const float s = ok ? sc[kb][r] * AC : -1e30f;
;       sc[kb][r] = s; mx = fmaxf(mx, s);
;     }
	v_min_u32_e32 v235, s6, v235
	v_lshlrev_b32_e32 v235, s71, v235
	v_add_u32_e32 v235, s79, v235
	v_mad_u32_u24 v235, v235, s62, v233
	global_load_dwordx4 v[228:231], v235, s[36:37]
	s_and_b64 vcc, vcc, s[4:5]
	v_subrev_u32_e32 v97, 62, v94
	v_add_u32_e32 v98, 2, v93
	v_cndmask_b32_e32 v65, v89, v65, vcc
	v_cmp_gt_u32_e32 vcc, s64, v98
	v_cmp_gt_u32_e64 s[4:5], s7, v97
	s_and_b64 vcc, vcc, s[4:5]
	v_subrev_u32_e32 v97, 61, v94
	v_add_u32_e32 v99, 3, v93
	v_cndmask_b32_e32 v66, v89, v66, vcc
	v_cmp_gt_u32_e32 vcc, s64, v99
	v_cmp_gt_u32_e64 s[4:5], s7, v97
	s_and_b64 vcc, vcc, s[4:5]
	v_subrev_u32_e32 v97, 56, v94
	v_add_u32_e32 v100, 8, v93
	v_cndmask_b32_e32 v67, v89, v67, vcc
	v_cmp_gt_u32_e32 vcc, s64, v100
	v_cmp_gt_u32_e64 s[4:5], s7, v97
	s_and_b64 vcc, vcc, s[4:5]
	v_subrev_u32_e32 v97, 55, v94
	v_add_u32_e32 v101, 9, v93
	v_cndmask_b32_e32 v68, v89, v68, vcc
	v_cmp_gt_u32_e32 vcc, s64, v101
	v_cmp_gt_u32_e64 s[4:5], s7, v97
	v_mfma_f32_32x32x16_bf16 v[0:15], v[102:105], v[126:129], v[0:15]
	s_and_b64 vcc, vcc, s[4:5]
	v_subrev_u32_e32 v97, 54, v94
	v_add_u32_e32 v102, 10, v93
	v_cndmask_b32_e32 v69, v89, v69, vcc
	v_cmp_gt_u32_e32 vcc, s64, v102
	v_cmp_gt_u32_e64 s[4:5], s7, v97
	s_and_b64 vcc, vcc, s[4:5]
	v_subrev_u32_e32 v97, 53, v94
	v_add_u32_e32 v103, 11, v93
	v_cndmask_b32_e32 v70, v89, v70, vcc
	v_cmp_gt_u32_e32 vcc, s64, v103
	v_cmp_gt_u32_e64 s[4:5], s7, v97
	v_mul_f32_e32 v71, 0x3e38aa3b, v71
	s_and_b64 vcc, vcc, s[4:5]
	v_subrev_u32_e32 v97, 48, v94
	v_add_u32_e32 v104, 16, v93
	v_cndmask_b32_e32 v71, v89, v71, vcc
	v_cmp_gt_u32_e32 vcc, s64, v104
	v_cmp_gt_u32_e64 s[4:5], s7, v97
	v_mul_f32_e32 v72, 0x3e38aa3b, v72
	s_and_b64 vcc, vcc, s[4:5]
	v_subrev_u32_e32 v97, 47, v94
	v_add_u32_e32 v105, 17, v93
	v_cndmask_b32_e32 v72, v89, v72, vcc
	v_cmp_gt_u32_e32 vcc, s64, v105
	v_cmp_gt_u32_e64 s[4:5], s7, v97
	v_mul_f32_e32 v73, 0x3e38aa3b, v73
	s_and_b64 vcc, vcc, s[4:5]
	v_subrev_u32_e32 v97, 46, v94
	v_add_u32_e32 v106, 18, v93
	v_cndmask_b32_e32 v73, v89, v73, vcc
	v_cmp_gt_u32_e32 vcc, s64, v106
	v_cmp_gt_u32_e64 s[4:5], s7, v97
	v_mul_f32_e32 v74, 0x3e38aa3b, v74
	s_and_b64 vcc, vcc, s[4:5]
	v_subrev_u32_e32 v97, 45, v94
	v_add_u32_e32 v107, 19, v93
	v_cndmask_b32_e32 v74, v89, v74, vcc
	v_cmp_gt_u32_e32 vcc, s64, v107
	v_cmp_gt_u32_e64 s[4:5], s7, v97
	v_mul_f32_e32 v75, 0x3e38aa3b, v75
	s_and_b64 vcc, vcc, s[4:5]
	v_subrev_u32_e32 v97, 40, v94
	v_add_u32_e32 v108, 24, v93
	v_cndmask_b32_e32 v75, v89, v75, vcc
	v_cmp_gt_u32_e32 vcc, s64, v108
	v_cmp_gt_u32_e64 s[4:5], s7, v97
	v_mul_f32_e32 v76, 0x3e38aa3b, v76
	s_and_b64 vcc, vcc, s[4:5]
	v_subrev_u32_e32 v97, 39, v94
	v_add_u32_e32 v109, 25, v93
	v_cndmask_b32_e32 v76, v89, v76, vcc
	v_cmp_gt_u32_e32 vcc, s64, v109
	v_cmp_gt_u32_e64 s[4:5], s7, v97
	v_mfma_f32_32x32x16_bf16 v[32:47], v[110:113], v[126:129], v[32:47]
	v_mul_f32_e32 v77, 0x3e38aa3b, v77
	s_and_b64 vcc, vcc, s[4:5]
	v_subrev_u32_e32 v97, 38, v94
	v_add_u32_e32 v110, 26, v93
	v_cndmask_b32_e32 v77, v89, v77, vcc
	v_cmp_gt_u32_e32 vcc, s64, v110
	v_cmp_gt_u32_e64 s[4:5], s7, v97
	v_mul_f32_e32 v78, 0x3e38aa3b, v78
	s_and_b64 vcc, vcc, s[4:5]
	v_subrev_u32_e32 v97, 37, v94
	v_add_u32_e32 v111, 27, v93
	v_cndmask_b32_e32 v78, v89, v78, vcc
	v_cmp_gt_u32_e32 vcc, s64, v111
	v_cmp_gt_u32_e64 s[4:5], s7, v97
	v_mul_f32_e32 v79, 0x3e38aa3b, v79
	s_and_b64 vcc, vcc, s[4:5]
	v_subrev_u32_e32 v97, 32, v94
	v_cndmask_b32_e32 v79, v89, v79, vcc
	v_cmp_gt_u32_e32 vcc, s7, v97
	v_subrev_u32_e32 v97, 31, v94
	v_max3_f32 v95, v64, s65, v65
	v_cndmask_b32_e32 v48, v89, v48, vcc
	v_cmp_gt_u32_e32 vcc, s7, v97
	v_subrev_u32_e32 v97, 30, v94
	v_mul_f32_e32 v53, 0x3e38aa3b, v53
	v_cndmask_b32_e32 v49, v89, v49, vcc
	v_cmp_gt_u32_e32 vcc, s7, v97
	v_subrev_u32_e32 v97, 29, v94
	v_max3_f32 v95, v95, v66, v67
	v_cndmask_b32_e32 v50, v89, v50, vcc
	v_cmp_gt_u32_e32 vcc, s7, v97
	v_subrev_u32_e32 v97, 24, v94
	v_mul_f32_e32 v54, 0x3e38aa3b, v54
	v_cndmask_b32_e32 v51, v89, v51, vcc
	v_cmp_gt_u32_e32 vcc, s7, v97
	v_subrev_u32_e32 v97, 23, v94
	v_max3_f32 v95, v95, v68, v69
	v_cndmask_b32_e32 v52, v89, v52, vcc
	v_cmp_gt_u32_e32 vcc, s7, v97
	v_subrev_u32_e32 v97, 22, v94
	v_mul_f32_e32 v55, 0x3e38aa3b, v55
	v_cndmask_b32_e32 v53, v89, v53, vcc
	v_cmp_gt_u32_e32 vcc, s7, v97
	v_subrev_u32_e32 v97, 21, v94
	v_max3_f32 v95, v95, v70, v71
	v_cndmask_b32_e32 v54, v89, v54, vcc
	v_cmp_gt_u32_e32 vcc, s7, v97
	v_add_u32_e32 v97, -16, v94
	v_mul_f32_e32 v56, 0x3e38aa3b, v56
	v_cndmask_b32_e32 v55, v89, v55, vcc
	v_cmp_gt_u32_e32 vcc, s7, v97
	v_add_u32_e32 v97, -15, v94
	v_max3_f32 v95, v95, v72, v73
	v_cndmask_b32_e32 v56, v89, v56, vcc
	v_mul_f32_e32 v57, 0x3e38aa3b, v57
	v_cmp_gt_u32_e32 vcc, s7, v97
	v_add_u32_e32 v97, -14, v94
	v_max3_f32 v95, v95, v74, v75
	v_cndmask_b32_e32 v57, v89, v57, vcc
	v_mul_f32_e32 v58, 0x3e38aa3b, v58
	v_cmp_gt_u32_e32 vcc, s7, v97
	v_add_u32_e32 v97, -13, v94
	v_max3_f32 v95, v95, v76, v77
	v_cndmask_b32_e32 v58, v89, v58, vcc
	v_mul_f32_e32 v59, 0x3e38aa3b, v59
	v_cmp_gt_u32_e32 vcc, s7, v97
	v_add_u32_e32 v97, -8, v94
	v_max3_f32 v95, v95, v78, v79
	v_cndmask_b32_e32 v59, v89, v59, vcc
	v_mul_f32_e32 v60, 0x3e38aa3b, v60
	v_cmp_gt_u32_e32 vcc, s7, v97
	v_add_u32_e32 v97, -7, v94
	v_max3_f32 v95, v95, v48, v49
	v_cndmask_b32_e32 v60, v89, v60, vcc
	v_mul_f32_e32 v61, 0x3e38aa3b, v61
	v_cmp_gt_u32_e32 vcc, s7, v97
	v_add_u32_e32 v97, -6, v94
	v_max3_f32 v95, v95, v50, v51
	v_cndmask_b32_e32 v61, v89, v61, vcc
	v_mul_f32_e32 v62, 0x3e38aa3b, v62
	v_cmp_gt_u32_e32 vcc, s7, v97
	v_add_u32_e32 v97, -5, v94
	v_max3_f32 v95, v95, v52, v53
	v_cndmask_b32_e32 v62, v89, v62, vcc
	v_mul_f32_e32 v63, 0x3e38aa3b, v63
; __device__ __forceinline__ int crow(int r, int hi) { return (r & 3) + 8 * (r >> 2) + 4 * hi; }
; __device__ __forceinline__ void dil_wave_item(const bf16* __restrict__ qkv, bf16* __restrict__ odil, float* __restrict__ lse,
;                               int pat, int g  , int head, char* wl  , const int W) {
;     ...
;   float mx = -1e30f;
; #pragma unroll
;   for (int kb = 0; kb < 5; ++kb)
; #pragma unroll
;     for (int r = 0; r < 16; ++r) {
;       const int rel = kb * 32 - 64 + crow(r, hi) - r32;
;       const int kc = i0 + r32 + rel;
;       const bool ok = (rel >= -64) && (rel <= 64) && (kc >= 0) && (kc < L);
;       const float s = ok ? sc[kb][r] * AC : -1e30f;
;       sc[kb][r] = s; mx = fmaxf(mx, s);
;     }
	v_cmp_gt_u32_e32 vcc, s7, v97
	v_max3_f32 v95, v95, v54, v55
	v_mul_f32_e32 v32, 0x3e38aa3b, v32
	v_cndmask_b32_e32 v63, v89, v63, vcc
	v_cmp_gt_u32_e32 vcc, s7, v94
	v_add_u32_e32 v96, v134, v96
	v_max3_f32 v95, v95, v56, v57
	v_cndmask_b32_e32 v32, v89, v32, vcc
	v_mul_f32_e32 v33, 0x3e38aa3b, v33
	v_cmp_gt_u32_e32 vcc, s7, v96
	v_add_u32_e32 v96, v134, v98
	v_max3_f32 v95, v95, v58, v59
	v_cndmask_b32_e32 v33, v89, v33, vcc
	v_mul_f32_e32 v34, 0x3e38aa3b, v34
	v_cmp_gt_u32_e32 vcc, s7, v96
	v_max3_f32 v95, v95, v60, v61
	v_max3_f32 v95, v95, v62, v63
	v_cndmask_b32_e32 v96, v89, v34, vcc
	v_add_u32_e32 v34, v134, v99
	v_mul_f32_e32 v35, 0x3e38aa3b, v35
	v_cmp_gt_u32_e32 vcc, s7, v34
	v_max3_f32 v95, v95, v32, v33
	v_mul_f32_e32 v36, 0x3e38aa3b, v36
	v_cndmask_b32_e32 v35, v89, v35, vcc
	v_max3_f32 v34, v95, v96, v35
	v_add_u32_e32 v95, v134, v100
	v_cmp_gt_u32_e32 vcc, s7, v95
	v_add_u32_e32 v95, v134, v101
	v_mul_f32_e32 v37, 0x3e38aa3b, v37
	v_cndmask_b32_e32 v36, v89, v36, vcc
	v_cmp_gt_u32_e32 vcc, s7, v95
	v_add_u32_e32 v95, v134, v102
	v_mul_f32_e32 v38, 0x3e38aa3b, v38
	v_cndmask_b32_e32 v37, v89, v37, vcc
	v_cmp_gt_u32_e32 vcc, s7, v95
	v_add_u32_e32 v95, v134, v103
	v_mul_f32_e32 v39, 0x3e38aa3b, v39
	v_cndmask_b32_e32 v38, v89, v38, vcc
	v_cmp_gt_u32_e32 vcc, s7, v95
	v_add_u32_e32 v95, v134, v104
	v_mfma_f32_32x32x16_bf16 v[16:31], v[114:117], v[126:129], v[16:31]
	v_cndmask_b32_e32 v39, v89, v39, vcc
	v_mul_f32_e32 v40, 0x3e38aa3b, v40
	v_cmp_gt_u32_e32 vcc, s7, v95
	v_add_u32_e32 v95, v134, v105
	v_mul_f32_e32 v41, 0x3e38aa3b, v41
	v_cndmask_b32_e32 v40, v89, v40, vcc
	v_cmp_gt_u32_e32 vcc, s7, v95
	v_add_u32_e32 v95, v134, v106
	v_mul_f32_e32 v42, 0x3e38aa3b, v42
	v_cndmask_b32_e32 v41, v89, v41, vcc
	v_cmp_gt_u32_e32 vcc, s7, v95
	v_add_u32_e32 v95, v134, v107
	v_mul_f32_e32 v43, 0x3e38aa3b, v43
	v_cndmask_b32_e32 v42, v89, v42, vcc
	v_cmp_gt_u32_e32 vcc, s7, v95
	v_add_u32_e32 v95, v134, v108
	v_mul_f32_e32 v44, 0x3e38aa3b, v44
	v_cndmask_b32_e32 v43, v89, v43, vcc
	v_cmp_gt_u32_e32 vcc, s7, v95
	v_add_u32_e32 v95, v134, v109
	v_mul_f32_e32 v45, 0x3e38aa3b, v45
	v_cndmask_b32_e32 v44, v89, v44, vcc
	v_cmp_gt_u32_e32 vcc, s7, v95
	v_add_u32_e32 v95, v134, v110
	v_mul_f32_e32 v46, 0x3e38aa3b, v46
	v_cndmask_b32_e32 v45, v89, v45, vcc
	v_cmp_gt_u32_e32 vcc, s7, v95
	v_add_u32_e32 v95, v134, v111
	v_mul_f32_e32 v47, 0x3e38aa3b, v47
	v_cndmask_b32_e32 v46, v89, v46, vcc
	v_cmp_gt_u32_e32 vcc, s7, v95
	v_add_u32_e32 v95, 32, v94
	v_mul_f32_e32 v16, 0x3e38aa3b, v16
	v_cndmask_b32_e32 v47, v89, v47, vcc
	v_cmp_gt_u32_e32 vcc, s7, v95
	v_add_u32_e32 v95, 33, v94
	v_mul_f32_e32 v17, 0x3e38aa3b, v17
	v_cndmask_b32_e32 v16, v89, v16, vcc
	v_cmp_gt_u32_e32 vcc, s7, v95
	v_add_u32_e32 v95, 34, v94
	v_mul_f32_e32 v18, 0x3e38aa3b, v18
	v_cndmask_b32_e32 v17, v89, v17, vcc
	v_cmp_gt_u32_e32 vcc, s7, v95
	v_add_u32_e32 v95, 35, v94
	v_mul_f32_e32 v19, 0x3e38aa3b, v19
	v_cndmask_b32_e32 v18, v89, v18, vcc
	v_cmp_gt_u32_e32 vcc, s7, v95
	v_add_u32_e32 v95, 40, v94
	v_mul_f32_e32 v20, 0x3e38aa3b, v20
	v_cndmask_b32_e32 v19, v89, v19, vcc
	v_cmp_gt_u32_e32 vcc, s7, v95
	v_add_u32_e32 v95, 41, v94
	v_mul_f32_e32 v21, 0x3e38aa3b, v21
	v_cndmask_b32_e32 v20, v89, v20, vcc
	v_cmp_gt_u32_e32 vcc, s7, v95
	v_add_u32_e32 v95, 42, v94
	v_mul_f32_e32 v22, 0x3e38aa3b, v22
	v_cndmask_b32_e32 v21, v89, v21, vcc
	v_cmp_gt_u32_e32 vcc, s7, v95
	v_add_u32_e32 v95, 43, v94
	v_mul_f32_e32 v23, 0x3e38aa3b, v23
	v_cndmask_b32_e32 v22, v89, v22, vcc
	v_cmp_gt_u32_e32 vcc, s7, v95
	v_add_u32_e32 v95, 48, v94
	v_max3_f32 v34, v34, v36, v37
	v_cndmask_b32_e32 v23, v89, v23, vcc
	v_mul_f32_e32 v24, 0x3e38aa3b, v24
	v_cmp_gt_u32_e32 vcc, s7, v95
	v_add_u32_e32 v95, 49, v94
	v_max3_f32 v34, v34, v38, v39
	v_cndmask_b32_e32 v24, v89, v24, vcc
	v_mul_f32_e32 v25, 0x3e38aa3b, v25
	v_cmp_gt_u32_e32 vcc, s7, v95
	v_add_u32_e32 v95, 50, v94
	v_max3_f32 v34, v34, v40, v41
	v_cndmask_b32_e32 v25, v89, v25, vcc
	v_mul_f32_e32 v26, 0x3e38aa3b, v26
	v_cmp_gt_u32_e32 vcc, s7, v95
	v_add_u32_e32 v95, 51, v94
	v_max3_f32 v34, v34, v42, v43
	v_cndmask_b32_e32 v26, v89, v26, vcc
	v_mul_f32_e32 v27, 0x3e38aa3b, v27
	v_cmp_gt_u32_e32 vcc, s7, v95
	v_add_u32_e32 v95, 56, v94
	v_max3_f32 v34, v34, v44, v45
	v_cndmask_b32_e32 v27, v89, v27, vcc
	v_mul_f32_e32 v28, 0x3e38aa3b, v28
	v_cmp_gt_u32_e32 vcc, s7, v95
	v_add_u32_e32 v95, 57, v94
	v_max3_f32 v34, v34, v46, v47
	v_cndmask_b32_e32 v28, v89, v28, vcc
	v_mul_f32_e32 v29, 0x3e38aa3b, v29
	v_cmp_gt_u32_e32 vcc, s7, v95
	v_add_u32_e32 v95, 58, v94
	v_max3_f32 v34, v34, v16, v17
	v_cndmask_b32_e32 v29, v89, v29, vcc
	v_mul_f32_e32 v30, 0x3e38aa3b, v30
	v_cmp_gt_u32_e32 vcc, s7, v95
	v_add_u32_e32 v95, 59, v94
	v_max3_f32 v34, v34, v18, v19
	v_cndmask_b32_e32 v30, v89, v30, vcc
	v_mul_f32_e32 v31, 0x3e38aa3b, v31
	v_cmp_gt_u32_e32 vcc, s7, v95
	v_add_u32_e32 v95, 64, v94
	v_add_u32_e32 v97, 0x80, v93
	v_max3_f32 v34, v34, v20, v21
	v_cndmask_b32_e32 v31, v89, v31, vcc
	v_cmp_gt_u32_e32 vcc, s64, v97
	v_cmp_gt_u32_e64 s[4:5], s7, v95
	v_max3_f32 v34, v34, v22, v23
	v_mul_f32_e32 v0, 0x3e38aa3b, v0
	s_and_b64 vcc, vcc, s[4:5]
	v_max3_f32 v34, v34, v24, v25
	v_cndmask_b32_e32 v98, v89, v0, vcc
	v_add_u32_e32 v0, 0x41, v94
	v_max3_f32 v34, v34, v26, v27
	v_cmp_lt_u32_e32 vcc, s68, v93
	v_cmp_gt_u32_e64 s[4:5], s7, v0
	v_max3_f32 v34, v34, v28, v29
	v_mul_f32_e32 v0, 0x3e38aa3b, v1
	s_and_b64 vcc, vcc, s[4:5]
	v_max3_f32 v34, v34, v30, v31
	v_cndmask_b32_e32 v99, v89, v0, vcc
	v_max3_f32 v0, v34, v98, v99
	v_add_u32_e32 v1, 0x42, v94
	v_add_u32_e32 v34, 0x82, v93
	v_cmp_gt_u32_e32 vcc, s64, v34
	v_cmp_gt_u32_e64 s[4:5], s7, v1
; __device__ __forceinline__ float shfl_idx(float v, int srclane) { return __int_as_float(__builtin_amdgcn_ds_bpermute(srclane << 2, __float_as_int(v))); }
; __device__ __forceinline__ int crow(int r, int hi) { return (r & 3) + 8 * (r >> 2) + 4 * hi; }
; __device__ __forceinline__ void dil_wave_item(const bf16* __restrict__ qkv, bf16* __restrict__ odil, float* __restrict__ lse,
;                               int pat, int g  , int head, char* wl  , const int W) {
;     ...
;   float mx = -1e30f;
; #pragma unroll
;   for (int kb = 0; kb < 5; ++kb)
; #pragma unroll
;     for (int r = 0; r < 16; ++r) {
;       const int rel = kb * 32 - 64 + crow(r, hi) - r32;
;       const int kc = i0 + r32 + rel;
;       const bool ok = (rel >= -64) && (rel <= 64) && (kc >= 0) && (kc < L);
;       const float s = ok ? sc[kb][r] * AC : -1e30f;
;       sc[kb][r] = s; mx = fmaxf(mx, s);
;     }
;   mx = fmaxf(mx, shfl_idx(mx, lane ^ 32));
;   float ls = 0.f;
; #pragma unroll
;   for (int kb = 0; kb < 5; ++kb)
; #pragma unroll
;     for (int r = 0; r < 16; ++r) { const float e = __builtin_amdgcn_exp2f(sc[kb][r] - mx); sc[kb][r] = e; ls += e; }
;   ls += shfl_idx(ls, lane ^ 32);
	v_mul_f32_e32 v1, 0x3e38aa3b, v2
	s_and_b64 vcc, vcc, s[4:5]
	v_cndmask_b32_e32 v100, v89, v1, vcc
	v_add_u32_e32 v1, 0x43, v94
	v_add_u32_e32 v2, 0x83, v93
	v_cmp_gt_u32_e32 vcc, s64, v2
	v_cmp_gt_u32_e64 s[4:5], s7, v1
	v_mul_f32_e32 v1, 0x3e38aa3b, v3
	s_and_b64 vcc, vcc, s[4:5]
	v_cndmask_b32_e32 v101, v89, v1, vcc
	v_add_u32_e32 v1, 0x48, v94
	v_add_u32_e32 v2, 0x88, v93
	v_cmp_gt_u32_e32 vcc, s64, v2
	v_cmp_gt_u32_e64 s[4:5], s7, v1
	v_mul_f32_e32 v1, 0x3e38aa3b, v4
	s_and_b64 vcc, vcc, s[4:5]
	v_cndmask_b32_e32 v102, v89, v1, vcc
	v_add_u32_e32 v1, 0x49, v94
	v_add_u32_e32 v2, 0x89, v93
	v_cmp_gt_u32_e32 vcc, s64, v2
	v_cmp_gt_u32_e64 s[4:5], s7, v1
	v_mul_f32_e32 v1, 0x3e38aa3b, v5
	s_and_b64 vcc, vcc, s[4:5]
	v_cndmask_b32_e32 v103, v89, v1, vcc
	v_add_u32_e32 v1, 0x4a, v94
	v_add_u32_e32 v2, 0x8a, v93
	v_cmp_gt_u32_e32 vcc, s64, v2
	v_cmp_gt_u32_e64 s[4:5], s7, v1
	v_mul_f32_e32 v1, 0x3e38aa3b, v6
	s_and_b64 vcc, vcc, s[4:5]
	v_cndmask_b32_e32 v104, v89, v1, vcc
	v_add_u32_e32 v1, 0x4b, v94
	v_add_u32_e32 v2, 0x8b, v93
	v_cmp_gt_u32_e32 vcc, s64, v2
	v_cmp_gt_u32_e64 s[4:5], s7, v1
	v_mul_f32_e32 v1, 0x3e38aa3b, v7
	s_and_b64 vcc, vcc, s[4:5]
	v_cndmask_b32_e32 v105, v89, v1, vcc
	v_add_u32_e32 v1, 0x50, v94
	v_add_u32_e32 v2, 0x90, v93
	v_cmp_gt_u32_e32 vcc, s64, v2
	v_cmp_gt_u32_e64 s[4:5], s7, v1
	v_mul_f32_e32 v1, 0x3e38aa3b, v8
	s_and_b64 vcc, vcc, s[4:5]
	v_cndmask_b32_e32 v106, v89, v1, vcc
	v_add_u32_e32 v1, 0x51, v94
	v_add_u32_e32 v2, 0x91, v93
	v_cmp_gt_u32_e32 vcc, s64, v2
	v_cmp_gt_u32_e64 s[4:5], s7, v1
	v_mul_f32_e32 v1, 0x3e38aa3b, v9
	s_and_b64 vcc, vcc, s[4:5]
	v_cndmask_b32_e32 v107, v89, v1, vcc
	v_add_u32_e32 v1, 0x52, v94
	v_add_u32_e32 v2, 0x92, v93
	v_cmp_gt_u32_e32 vcc, s64, v2
	v_cmp_gt_u32_e64 s[4:5], s7, v1
	v_mul_f32_e32 v1, 0x3e38aa3b, v10
	s_and_b64 vcc, vcc, s[4:5]
	v_cndmask_b32_e32 v108, v89, v1, vcc
	v_add_u32_e32 v1, 0x53, v94
	v_add_u32_e32 v2, 0x93, v93
	v_cmp_gt_u32_e32 vcc, s64, v2
	v_cmp_gt_u32_e64 s[4:5], s7, v1
	v_mul_f32_e32 v1, 0x3e38aa3b, v11
	s_and_b64 vcc, vcc, s[4:5]
	v_cndmask_b32_e32 v109, v89, v1, vcc
	v_add_u32_e32 v1, 0x58, v94
	v_add_u32_e32 v2, 0x98, v93
	v_cmp_gt_u32_e32 vcc, s64, v2
	v_cmp_gt_u32_e64 s[4:5], s7, v1
	v_mul_f32_e32 v1, 0x3e38aa3b, v12
	s_and_b64 vcc, vcc, s[4:5]
	v_cndmask_b32_e32 v110, v89, v1, vcc
	v_add_u32_e32 v1, 0x59, v94
	v_add_u32_e32 v2, 0x99, v93
	v_cmp_gt_u32_e32 vcc, s64, v2
	v_cmp_gt_u32_e64 s[4:5], s7, v1
	v_mul_f32_e32 v1, 0x3e38aa3b, v13
	s_and_b64 vcc, vcc, s[4:5]
	v_cndmask_b32_e32 v111, v89, v1, vcc
	v_add_u32_e32 v1, 0x5a, v94
	v_add_u32_e32 v2, 0x9a, v93
	v_max3_f32 v0, v0, v100, v101
	v_cmp_gt_u32_e32 vcc, s64, v2
	v_cmp_gt_u32_e64 s[4:5], s7, v1
	v_max3_f32 v0, v0, v102, v103
	v_mul_f32_e32 v1, 0x3e38aa3b, v14
	s_and_b64 vcc, vcc, s[4:5]
	v_max3_f32 v0, v0, v104, v105
	v_cndmask_b32_e32 v112, v89, v1, vcc
	v_add_u32_e32 v1, 0x5b, v94
	v_add_u32_e32 v2, 0x9b, v93
	v_max3_f32 v0, v0, v106, v107
	v_cmp_gt_u32_e32 vcc, s64, v2
	v_cmp_gt_u32_e64 s[4:5], s7, v1
	v_max3_f32 v0, v0, v108, v109
	v_mul_f32_e32 v1, 0x3e38aa3b, v15
	s_and_b64 vcc, vcc, s[4:5]
	v_max3_f32 v0, v0, v110, v111
	v_cndmask_b32_e32 v113, v89, v1, vcc
	v_lshlrev_b32_e32 v1, 2, v87
	v_max3_f32 v0, v0, v112, v113
	v_xor_b32_e32 v114, 0x80, v1
	ds_bpermute_b32 v1, v114, v0
	s_waitcnt lgkmcnt(0)
	v_max_f32_e32 v1, v1, v1
	v_max_f32_e32 v34, v0, v1
	v_sub_f32_e32 v0, v64, v34
	v_exp_f32_e32 v115, v0
	v_sub_f32_e32 v0, v65, v34
	v_exp_f32_e32 v116, v0
	v_sub_f32_e32 v0, v66, v34
	v_exp_f32_e32 v117, v0
	v_sub_f32_e32 v0, v67, v34
	v_exp_f32_e32 v118, v0
	v_sub_f32_e32 v1, v68, v34
	v_add_f32_e32 v0, 0, v115
	v_exp_f32_e32 v119, v1
	v_sub_f32_e32 v1, v69, v34
	v_add_f32_e32 v0, v116, v0
	v_exp_f32_e32 v120, v1
	v_sub_f32_e32 v1, v70, v34
	v_add_f32_e32 v0, v117, v0
	v_exp_f32_e32 v121, v1
	v_sub_f32_e32 v1, v71, v34
	v_add_f32_e32 v0, v118, v0
	v_exp_f32_e32 v122, v1
	v_sub_f32_e32 v1, v72, v34
	v_add_f32_e32 v0, v119, v0
	v_exp_f32_e32 v123, v1
	v_sub_f32_e32 v1, v73, v34
	v_add_f32_e32 v0, v120, v0
	v_exp_f32_e32 v124, v1
	v_sub_f32_e32 v1, v74, v34
	v_add_f32_e32 v0, v121, v0
	v_exp_f32_e32 v125, v1
	v_sub_f32_e32 v1, v75, v34
	v_add_f32_e32 v0, v122, v0
	v_exp_f32_e32 v126, v1
	v_sub_f32_e32 v1, v76, v34
	v_add_f32_e32 v0, v123, v0
	v_exp_f32_e32 v127, v1
	v_sub_f32_e32 v1, v77, v34
	v_add_f32_e32 v0, v124, v0
	v_exp_f32_e32 v128, v1
	v_sub_f32_e32 v1, v78, v34
	v_add_f32_e32 v0, v125, v0
	v_exp_f32_e32 v129, v1
	v_sub_f32_e32 v1, v79, v34
	v_add_f32_e32 v0, v126, v0
	v_exp_f32_e32 v130, v1
	v_sub_f32_e32 v1, v48, v34
	v_add_f32_e32 v0, v127, v0
	v_exp_f32_e32 v131, v1
	v_sub_f32_e32 v1, v49, v34
	v_add_f32_e32 v0, v128, v0
	v_exp_f32_e32 v132, v1
	v_sub_f32_e32 v1, v50, v34
	v_add_f32_e32 v0, v129, v0
	v_exp_f32_e32 v133, v1
	v_sub_f32_e32 v1, v51, v34
	v_add_f32_e32 v0, v130, v0
	v_exp_f32_e32 v134, v1
	v_sub_f32_e32 v1, v52, v34
	v_add_f32_e32 v0, v131, v0
	v_exp_f32_e32 v135, v1
	v_sub_f32_e32 v1, v53, v34
	v_add_f32_e32 v0, v132, v0
	v_exp_f32_e32 v136, v1
	v_sub_f32_e32 v1, v54, v34
	v_add_f32_e32 v0, v133, v0
	v_exp_f32_e32 v137, v1
	v_sub_f32_e32 v1, v55, v34
	v_add_f32_e32 v0, v134, v0
	v_exp_f32_e32 v138, v1
	v_sub_f32_e32 v1, v56, v34
	v_add_f32_e32 v0, v135, v0
	v_exp_f32_e32 v139, v1
	v_sub_f32_e32 v1, v57, v34
	v_add_f32_e32 v0, v136, v0
	v_exp_f32_e32 v140, v1
	v_sub_f32_e32 v1, v58, v34
	v_add_f32_e32 v0, v137, v0
	v_exp_f32_e32 v141, v1
	v_sub_f32_e32 v1, v59, v34
	v_add_f32_e32 v0, v138, v0
	v_exp_f32_e32 v142, v1
	v_sub_f32_e32 v1, v60, v34
	v_add_f32_e32 v0, v139, v0
	v_exp_f32_e32 v143, v1
	v_sub_f32_e32 v1, v61, v34
	v_add_f32_e32 v0, v140, v0
; __device__ __forceinline__ float shfl_idx(float v, int srclane) { return __int_as_float(__builtin_amdgcn_ds_bpermute(srclane << 2, __float_as_int(v))); }
; __device__ __forceinline__ int v_st2(int k, int c) { const int kk = (k & ~0xC) | ((k & 4) << 1) | ((k & 8) >> 1); return ((kk >> 3) * 2 + (c >> 5)) * 512 + ((kk & 7) * 32 + (c & 31)) * 2; }
; __device__ __forceinline__ int v_rd_base(int lane) { return ((lane & 3) << 3) | (((lane >> 2) & 3) << 6) | (((lane >> 4) & 1) << 5) | (((lane >> 5) & 1) << 8); }
; __device__ __forceinline__ void dil_wave_item(const bf16* __restrict__ qkv, bf16* __restrict__ odil, float* __restrict__ lse,
;                               int pat, int g  , int head, char* wl  , const int W) {
;     ...
;   float ls = 0.f;
; #pragma unroll
;   for (int kb = 0; kb < 5; ++kb)
; #pragma unroll
;     for (int r = 0; r < 16; ++r) { const float e = __builtin_amdgcn_exp2f(sc[kb][r] - mx); sc[kb][r] = e; ls += e; }
;   ls += shfl_idx(ls, lane ^ 32);
;   f32x16 o0 = {}, o1 = {};
;   const int vb = (int)(uintptr_t)wl + v_rd_base(lane);
; #pragma unroll
;   for (int kb = 0; kb < 5; ++kb) {
;     bf16x8 vr[4];
; #pragma unroll
;     for (int i = 0; i < 4; ++i) {
;       const int key = i * 8 + (lane >> 3);
;       int kc = i0 - 64 + kb * 32 + key; kc = min(max(kc, 0), L - 1);
;       vr[i] = *reinterpret_cast<const bf16x8*>(qkv + (size_t)(tbase + kc * dil) * LDQ + 2560 + head * 64 + (lane & 7) * 8);
;     }
; #pragma unroll
;     for (int i = 0; i < 4; ++i) *reinterpret_cast<bf16x8*>(wl + v_st2(i * 8 + (lane >> 3), (lane & 7) * 8)) = vr[i];
	v_exp_f32_e32 v144, v1
	v_sub_f32_e32 v1, v62, v34
	v_add_f32_e32 v0, v141, v0
	v_exp_f32_e32 v145, v1
	v_sub_f32_e32 v1, v63, v34
	v_add_f32_e32 v0, v142, v0
	v_exp_f32_e32 v146, v1
	v_sub_f32_e32 v1, v32, v34
	v_add_f32_e32 v0, v143, v0
	v_exp_f32_e32 v56, v1
	v_sub_f32_e32 v1, v33, v34
	v_add_f32_e32 v0, v144, v0
	v_exp_f32_e32 v57, v1
	v_sub_f32_e32 v1, v96, v34
	v_add_f32_e32 v0, v145, v0
	v_exp_f32_e32 v60, v1
	v_sub_f32_e32 v1, v35, v34
	v_add_f32_e32 v0, v146, v0
	v_exp_f32_e32 v65, v1
	v_sub_f32_e32 v1, v36, v34
	v_add_f32_e32 v0, v56, v0
	v_exp_f32_e32 v69, v1
	v_sub_f32_e32 v1, v37, v34
	v_add_f32_e32 v0, v57, v0
	v_exp_f32_e32 v71, v1
	v_sub_f32_e32 v1, v38, v34
	v_add_f32_e32 v0, v60, v0
	v_exp_f32_e32 v75, v1
	v_sub_f32_e32 v1, v39, v34
	v_add_f32_e32 v0, v65, v0
	v_exp_f32_e32 v78, v1
	v_sub_f32_e32 v1, v40, v34
	v_add_f32_e32 v0, v69, v0
	v_exp_f32_e32 v72, v1
	v_sub_f32_e32 v1, v41, v34
	v_add_f32_e32 v0, v71, v0
	v_exp_f32_e32 v76, v1
	v_sub_f32_e32 v1, v42, v34
	v_add_f32_e32 v0, v75, v0
	v_exp_f32_e32 v79, v1
	v_sub_f32_e32 v1, v43, v34
	v_add_f32_e32 v0, v78, v0
	v_exp_f32_e32 v93, v1
	v_sub_f32_e32 v1, v44, v34
	v_add_f32_e32 v0, v72, v0
	v_exp_f32_e32 v94, v1
	v_sub_f32_e32 v1, v45, v34
	v_add_f32_e32 v0, v76, v0
	v_exp_f32_e32 v95, v1
	v_sub_f32_e32 v1, v46, v34
	v_add_f32_e32 v0, v79, v0
	v_exp_f32_e32 v96, v1
	v_sub_f32_e32 v1, v47, v34
	v_add_f32_e32 v0, v93, v0
	v_exp_f32_e32 v97, v1
	v_sub_f32_e32 v1, v16, v34
	v_add_f32_e32 v0, v94, v0
	v_exp_f32_e32 v35, v1
	v_sub_f32_e32 v1, v17, v34
	v_add_f32_e32 v0, v95, v0
	v_exp_f32_e32 v36, v1
	v_sub_f32_e32 v1, v18, v34
	v_add_f32_e32 v0, v96, v0
	v_exp_f32_e32 v37, v1
	v_sub_f32_e32 v1, v19, v34
	v_add_f32_e32 v0, v97, v0
	v_exp_f32_e32 v38, v1
	v_sub_f32_e32 v1, v20, v34
	v_add_f32_e32 v0, v35, v0
	v_exp_f32_e32 v42, v1
	v_sub_f32_e32 v1, v21, v34
	v_add_f32_e32 v0, v36, v0
	v_exp_f32_e32 v43, v1
	v_sub_f32_e32 v1, v22, v34
	v_add_f32_e32 v0, v37, v0
	v_exp_f32_e32 v45, v1
	v_sub_f32_e32 v1, v23, v34
	v_add_f32_e32 v0, v38, v0
	v_exp_f32_e32 v47, v1
	v_sub_f32_e32 v1, v24, v34
	v_add_f32_e32 v0, v42, v0
	v_exp_f32_e32 v44, v1
	v_sub_f32_e32 v1, v25, v34
	v_add_f32_e32 v0, v43, v0
	v_exp_f32_e32 v46, v1
	v_sub_f32_e32 v1, v26, v34
	v_add_f32_e32 v0, v45, v0
	v_exp_f32_e32 v48, v1
	v_sub_f32_e32 v1, v27, v34
	v_add_f32_e32 v0, v47, v0
	v_exp_f32_e32 v49, v1
	v_add_f32_e32 v0, v44, v0
	v_add_f32_e32 v0, v46, v0
	v_add_f32_e32 v0, v48, v0
	v_bfe_u32 v17, v92, 3, 3
	v_add_f32_e32 v16, v49, v0
	v_sub_f32_e32 v0, v28, v34
	v_or_b32_e32 v10, s78, v17
	v_exp_f32_e32 v50, v0
	v_sub_f32_e32 v0, v29, v34
	v_subrev_u32_e32 v39, 64, v10
	v_lshlrev_b32_e32 v18, 3, v92
	v_exp_f32_e32 v51, v0
	v_and_b32_e32 v2, 56, v18
	v_max_i32_e32 v0, 0, v39
	v_min_u32_e32 v0, s6, v0
	v_lshlrev_b32_e32 v32, 1, v2
	v_subrev_u32_e32 v2, 56, v10
	v_lshlrev_b32_e32 v0, s71, v0
	v_max_i32_e32 v2, 0, v2
	v_add_u32_e32 v0, s79, v0
	v_min_u32_e32 v2, s6, v2
	v_subrev_u32_e32 v8, 48, v10
	v_mad_i64_i32 v[0:1], s[4:5], v0, s62, v[84:85]
	v_lshlrev_b32_e32 v2, s71, v2
	v_max_i32_e32 v8, 0, v8
	v_lshl_add_u64 v[0:1], v[0:1], 0, s[74:75]
	v_mov_b32_e32 v33, v83
	v_add_u32_e32 v2, s79, v2
	v_min_u32_e32 v8, s6, v8
	v_subrev_u32_e32 v10, 40, v10
	v_lshl_add_u64 v[0:1], v[0:1], 0, v[32:33]
	v_mad_i64_i32 v[2:3], s[4:5], v2, s62, v[84:85]
	v_lshlrev_b32_e32 v8, s71, v8
	v_max_i32_e32 v10, 0, v10
	v_add_co_u32_e32 v0, vcc, s63, v0
	v_lshl_add_u64 v[2:3], v[2:3], 0, s[74:75]
	v_add_u32_e32 v8, s79, v8
	v_min_u32_e32 v10, s6, v10
	v_addc_co_u32_e32 v1, vcc, 0, v1, vcc
	v_lshl_add_u64 v[2:3], v[2:3], 0, v[32:33]
	v_mad_i64_i32 v[8:9], s[4:5], v8, s62, v[84:85]
	v_lshlrev_b32_e32 v10, s71, v10
	v_add_co_u32_e32 v4, vcc, s63, v2
	v_lshl_add_u64 v[8:9], v[8:9], 0, s[74:75]
	v_add_u32_e32 v10, s79, v10
	v_addc_co_u32_e32 v5, vcc, 0, v3, vcc
	v_lshl_add_u64 v[8:9], v[8:9], 0, v[32:33]
	v_mad_i64_i32 v[10:11], s[4:5], v10, s62, v[84:85]
	v_add_co_u32_e32 v8, vcc, s63, v8
	v_lshl_add_u64 v[10:11], v[10:11], 0, s[74:75]
	s_nop 0
	v_addc_co_u32_e32 v9, vcc, 0, v9, vcc
	v_lshl_add_u64 v[10:11], v[10:11], 0, v[32:33]
	v_add_co_u32_e32 v12, vcc, s63, v10
	s_nop 0
	v_addc_co_u32_e32 v13, vcc, 0, v11, vcc
	s_nop 0
	v_sub_f32_e32 v19, v30, v34
	v_exp_f32_e32 v147, v19
	v_sub_f32_e32 v19, v31, v34
	v_exp_f32_e32 v148, v19
	v_sub_f32_e32 v19, v98, v34
	v_add_f32_e32 v16, v50, v16
	v_exp_f32_e32 v52, v19
	v_sub_f32_e32 v19, v99, v34
	v_add_f32_e32 v16, v51, v16
	v_exp_f32_e32 v53, v19
	v_sub_f32_e32 v19, v100, v34
	v_add_f32_e32 v16, v147, v16
	v_exp_f32_e32 v54, v19
	v_sub_f32_e32 v19, v101, v34
	v_add_f32_e32 v16, v148, v16
	v_exp_f32_e32 v55, v19
	v_sub_f32_e32 v19, v102, v34
	v_add_f32_e32 v16, v52, v16
	v_exp_f32_e32 v58, v19
	v_sub_f32_e32 v19, v103, v34
	v_add_f32_e32 v16, v53, v16
	v_exp_f32_e32 v61, v19
	v_sub_f32_e32 v19, v104, v34
	v_add_f32_e32 v16, v54, v16
	v_exp_f32_e32 v63, v19
	v_sub_f32_e32 v19, v105, v34
	v_add_f32_e32 v16, v55, v16
	v_exp_f32_e32 v66, v19
	v_sub_f32_e32 v19, v106, v34
	v_add_f32_e32 v16, v58, v16
	v_exp_f32_e32 v59, v19
	v_sub_f32_e32 v19, v107, v34
	v_add_f32_e32 v16, v61, v16
	v_exp_f32_e32 v62, v19
	v_sub_f32_e32 v19, v108, v34
	v_add_f32_e32 v16, v63, v16
	v_exp_f32_e32 v64, v19
	v_sub_f32_e32 v19, v109, v34
	v_add_f32_e32 v16, v66, v16
	v_exp_f32_e32 v67, v19
	v_sub_f32_e32 v19, v110, v34
	v_add_f32_e32 v16, v59, v16
	v_exp_f32_e32 v70, v19
	v_sub_f32_e32 v19, v111, v34
	v_add_f32_e32 v16, v62, v16
	v_exp_f32_e32 v73, v19
	v_sub_f32_e32 v19, v112, v34
	v_add_f32_e32 v16, v64, v16
	v_exp_f32_e32 v74, v19
	v_sub_f32_e32 v19, v113, v34
	v_add_f32_e32 v16, v67, v16
	v_exp_f32_e32 v77, v19
	v_add_f32_e32 v16, v70, v16
	v_add_f32_e32 v16, v73, v16
	v_add_f32_e32 v16, v74, v16
	v_lshlrev_b32_e32 v19, 4, v92
	v_add_f32_e32 v40, v77, v16
	v_lshlrev_b32_e32 v16, 3, v87
	v_and_b32_e32 v20, 0xc0, v19
	v_lshlrev_b32_e32 v21, 1, v92
	v_and_or_b32 v20, v16, 24, v20
	v_and_b32_e32 v21, 32, v21
	v_and_b32_e32 v16, 0x100, v16
	v_or3_b32 v16, v20, v21, v16
	v_add_u32_e32 v68, s55, v16
	v_bfe_u32 v16, v18, 5, 1
	v_and_b32_e32 v18, 48, v19
	v_lshrrev_b32_e32 v19, 4, v92
	v_and_or_b32 v16, v19, 2, v16
	v_lshlrev_b32_e32 v17, 6, v17
	v_and_or_b32 v19, v17, s69, v18
	v_lshl_add_u32 v16, v16, 9, s55
	v_add_u32_e32 v149, v16, v19
	ds_bpermute_b32 v41, v114, v40
	s_waitcnt vmcnt(16)
; #define SBAR() __builtin_amdgcn_sched_barrier(0)
; __device__ __forceinline__ int v_st2(int k, int c) { const int kk = (k & ~0xC) | ((k & 4) << 1) | ((k & 8) >> 1); return ((kk >> 3) * 2 + (c >> 5)) * 512 + ((kk & 7) * 32 + (c & 31)) * 2; }
; __device__ __forceinline__ void dil_wave_item(const bf16* __restrict__ qkv, bf16* __restrict__ odil, float* __restrict__ lse,
;                               int pat, int g  , int head, char* wl  , const int W) {
;     ...
; #pragma unroll
;   for (int kb = 0; kb < 5; ++kb) {
;     bf16x8 vr[4];
; #pragma unroll
;     for (int i = 0; i < 4; ++i) {
;       const int key = i * 8 + (lane >> 3);
;       int kc = i0 - 64 + kb * 32 + key; kc = min(max(kc, 0), L - 1);
;       vr[i] = *reinterpret_cast<const bf16x8*>(qkv + (size_t)(tbase + kc * dil) * LDQ + 2560 + head * 64 + (lane & 7) * 8);
;     }
; #pragma unroll
;     for (int i = 0; i < 4; ++i) *reinterpret_cast<bf16x8*>(wl + v_st2(i * 8 + (lane >> 3), (lane & 7) * 8)) = vr[i];
;     bf16x8 pa0, pa1;
;     PK4(sc[kb], 0, pa0); PK4(sc[kb], 8, pa1);
;     asm volatile("s_waitcnt lgkmcnt(0)" ::: "memory");
;     const s16x4 a0 = tr_read<v_rd_off2(0, 0, 0)>(vb), b0 = tr_read<v_rd_off2(0, 0, 1)>(vb), a1 = tr_read<v_rd_off2(0, 1, 0)>(vb), b1 = tr_read<v_rd_off2(0, 1, 1)>(vb);
;     const s16x4 c0 = tr_read<v_rd_off2(1, 0, 0)>(vb), d0_ = tr_read<v_rd_off2(1, 0, 1)>(vb), c1 = tr_read<v_rd_off2(1, 1, 0)>(vb), d1 = tr_read<v_rd_off2(1, 1, 1)>(vb);
;     asm volatile("s_waitcnt lgkmcnt(0)" ::: "memory"); SBAR();
;     o0 = __builtin_amdgcn_mfma_f32_32x32x16_bf16(pa0, PKV(a0, b0), o0, 0, 0, 0);
;     o0 = __builtin_amdgcn_mfma_f32_32x32x16_bf16(pa1, PKV(a1, b1), o0, 0, 0, 0);
;     o1 = __builtin_amdgcn_mfma_f32_32x32x16_bf16(pa0, PKV(c0, d0_), o1, 0, 0, 0);
;     o1 = __builtin_amdgcn_mfma_f32_32x32x16_bf16(pa1, PKV(c1, d1), o1, 0, 0, 0);
;     SBAR();
;   }
;   if (hi == 0) lse[((size_t)pat * T + tbase + (i0 + r32) * dil) * 8 + head] = mx + __log2f(ls);
	ds_write_b128 v149, v[152:155]
	v_or3_b32 v0, v17, v18, s61
	v_add_u32_e32 v150, v16, v0
	ds_write_b128 v150, v[156:159]
	ds_write_b128 v149, v[160:163] offset:2048
	ds_write_b128 v150, v[164:167] offset:2048
	v_cvt_pk_bf16_f32 v16, v115, v116
	v_cvt_pk_bf16_f32 v17, v117, v118
	v_cvt_pk_bf16_f32 v18, v119, v120
	v_cvt_pk_bf16_f32 v19, v121, v122
	v_cvt_pk_bf16_f32 v98, v123, v124
	v_cvt_pk_bf16_f32 v99, v125, v126
	v_cvt_pk_bf16_f32 v100, v127, v128
	v_cvt_pk_bf16_f32 v101, v129, v130
	s_waitcnt lgkmcnt(0)
	ds_read_b64_tr_b16 v[0:1], v68 offset:0
	ds_read_b64_tr_b16 v[2:3], v68 offset:0x400
	ds_read_b64_tr_b16 v[20:21], v68 offset:0x800
	ds_read_b64_tr_b16 v[22:23], v68 offset:0xc00
	ds_read_b64_tr_b16 v[24:25], v68 offset:0x200
	ds_read_b64_tr_b16 v[26:27], v68 offset:0x600
	ds_read_b64_tr_b16 v[102:103], v68 offset:0xa00
	ds_read_b64_tr_b16 v[104:105], v68 offset:0xe00
	s_waitcnt lgkmcnt(0)
	s_nop 0
	v_permlane32_swap_b32_e32 v16, v18
	v_permlane32_swap_b32_e32 v17, v19
	v_permlane32_swap_b32_e32 v98, v100
	v_permlane32_swap_b32_e32 v99, v101
	v_mfma_f32_32x32x16_bf16 v[0:15], v[16:19], v[0:3], 0
	s_nop 0
	v_mfma_f32_32x32x16_bf16 v[0:15], v[98:101], v[20:23], v[0:15]
	v_mfma_f32_32x32x16_bf16 v[16:31], v[16:19], v[24:27], 0
	v_mfma_f32_32x32x16_bf16 v[16:31], v[98:101], v[102:105], v[16:31]
	s_waitcnt vmcnt(12)
	ds_write_b128 v149, v[168:171]
	ds_write_b128 v150, v[172:175]
	ds_write_b128 v149, v[176:179] offset:2048
	ds_write_b128 v150, v[180:183] offset:2048
	v_cvt_pk_bf16_f32 v98, v131, v132
	v_cvt_pk_bf16_f32 v99, v133, v134
	v_cvt_pk_bf16_f32 v100, v135, v136
	v_cvt_pk_bf16_f32 v101, v137, v138
	v_cvt_pk_bf16_f32 v102, v139, v140
	v_cvt_pk_bf16_f32 v103, v141, v142
	v_cvt_pk_bf16_f32 v104, v143, v144
	v_cvt_pk_bf16_f32 v105, v145, v146
	s_waitcnt lgkmcnt(0)
	ds_read_b64_tr_b16 v[106:107], v68 offset:0
	ds_read_b64_tr_b16 v[108:109], v68 offset:0x400
	ds_read_b64_tr_b16 v[110:111], v68 offset:0x800
	ds_read_b64_tr_b16 v[112:113], v68 offset:0xc00
	ds_read_b64_tr_b16 v[114:115], v68 offset:0x200
	ds_read_b64_tr_b16 v[116:117], v68 offset:0x600
	ds_read_b64_tr_b16 v[118:119], v68 offset:0xa00
	ds_read_b64_tr_b16 v[120:121], v68 offset:0xe00
	s_waitcnt lgkmcnt(0)
	s_nop 0
	v_permlane32_swap_b32_e32 v98, v100
	v_permlane32_swap_b32_e32 v99, v101
	v_permlane32_swap_b32_e32 v102, v104
	v_permlane32_swap_b32_e32 v103, v105
	v_mfma_f32_32x32x16_bf16 v[0:15], v[98:101], v[106:109], v[0:15]
	v_mfma_f32_32x32x16_bf16 v[16:31], v[98:101], v[114:117], v[16:31]
	v_mfma_f32_32x32x16_bf16 v[0:15], v[102:105], v[110:113], v[0:15]
	v_mfma_f32_32x32x16_bf16 v[16:31], v[102:105], v[118:121], v[16:31]
	s_waitcnt vmcnt(8)
	ds_write_b128 v149, v[184:187]
	ds_write_b128 v150, v[188:191]
	ds_write_b128 v149, v[192:195] offset:2048
	ds_write_b128 v150, v[196:199] offset:2048
	v_cvt_pk_bf16_f32 v98, v56, v57
	v_cvt_pk_bf16_f32 v99, v60, v65
	v_cvt_pk_bf16_f32 v100, v69, v71
	v_cvt_pk_bf16_f32 v101, v75, v78
	v_cvt_pk_bf16_f32 v92, v72, v76
	v_cvt_pk_bf16_f32 v93, v79, v93
	v_cvt_pk_bf16_f32 v94, v94, v95
	v_cvt_pk_bf16_f32 v95, v96, v97
	s_waitcnt lgkmcnt(0)
	ds_read_b64_tr_b16 v[102:103], v68 offset:0
	ds_read_b64_tr_b16 v[104:105], v68 offset:0x400
	ds_read_b64_tr_b16 v[106:107], v68 offset:0x800
	ds_read_b64_tr_b16 v[108:109], v68 offset:0xc00
	ds_read_b64_tr_b16 v[110:111], v68 offset:0x200
	ds_read_b64_tr_b16 v[112:113], v68 offset:0x600
	ds_read_b64_tr_b16 v[114:115], v68 offset:0xa00
	ds_read_b64_tr_b16 v[116:117], v68 offset:0xe00
	s_waitcnt lgkmcnt(0)
	s_nop 0
	v_permlane32_swap_b32_e32 v98, v100
	v_permlane32_swap_b32_e32 v99, v101
	v_permlane32_swap_b32_e32 v92, v94
	v_permlane32_swap_b32_e32 v93, v95
	v_mfma_f32_32x32x16_bf16 v[0:15], v[98:101], v[102:105], v[0:15]
	v_mfma_f32_32x32x16_bf16 v[16:31], v[98:101], v[110:113], v[16:31]
	v_mfma_f32_32x32x16_bf16 v[0:15], v[92:95], v[106:109], v[0:15]
	v_mfma_f32_32x32x16_bf16 v[16:31], v[92:95], v[114:117], v[16:31]
	s_waitcnt vmcnt(4)
	ds_write_b128 v149, v[200:203]
	ds_write_b128 v150, v[204:207]
	ds_write_b128 v149, v[208:211] offset:2048
	ds_write_b128 v150, v[212:215] offset:2048
	v_cvt_pk_bf16_f32 v92, v35, v36
	v_cvt_pk_bf16_f32 v93, v37, v38
	v_cvt_pk_bf16_f32 v94, v42, v43
	v_cvt_pk_bf16_f32 v95, v45, v47
	v_cvt_pk_bf16_f32 v42, v44, v46
	v_cvt_pk_bf16_f32 v43, v48, v49
	v_cvt_pk_bf16_f32 v44, v50, v51
	v_cvt_pk_bf16_f32 v45, v147, v148
	s_waitcnt lgkmcnt(0)
	ds_read_b64_tr_b16 v[46:47], v68 offset:0
	ds_read_b64_tr_b16 v[48:49], v68 offset:0x400
	ds_read_b64_tr_b16 v[96:97], v68 offset:0x800
	ds_read_b64_tr_b16 v[98:99], v68 offset:0xc00
	ds_read_b64_tr_b16 v[100:101], v68 offset:0x200
	ds_read_b64_tr_b16 v[102:103], v68 offset:0x600
	ds_read_b64_tr_b16 v[104:105], v68 offset:0xa00
	ds_read_b64_tr_b16 v[106:107], v68 offset:0xe00
	s_waitcnt lgkmcnt(0)
	s_nop 0
	v_permlane32_swap_b32_e32 v92, v94
	v_permlane32_swap_b32_e32 v93, v95
	v_permlane32_swap_b32_e32 v42, v44
	v_permlane32_swap_b32_e32 v43, v45
	v_mfma_f32_32x32x16_bf16 v[0:15], v[92:95], v[46:49], v[0:15]
	v_mfma_f32_32x32x16_bf16 v[16:31], v[92:95], v[100:103], v[16:31]
	v_mfma_f32_32x32x16_bf16 v[0:15], v[42:45], v[96:99], v[0:15]
	v_mfma_f32_32x32x16_bf16 v[16:31], v[42:45], v[104:107], v[16:31]
	s_waitcnt vmcnt(0)
	ds_write_b128 v149, v[216:219]
	ds_write_b128 v150, v[220:223]
	ds_write_b128 v149, v[224:227] offset:2048
	ds_write_b128 v150, v[228:231] offset:2048
	v_cvt_pk_bf16_f32 v36, v52, v53
	v_cvt_pk_bf16_f32 v37, v54, v55
	v_cvt_pk_bf16_f32 v38, v58, v61
	v_cvt_pk_bf16_f32 v39, v63, v66
	v_cvt_pk_bf16_f32 v42, v59, v62
	v_cvt_pk_bf16_f32 v43, v64, v67
	v_cvt_pk_bf16_f32 v44, v70, v73
	v_cvt_pk_bf16_f32 v45, v74, v77
	s_waitcnt lgkmcnt(0)
	ds_read_b64_tr_b16 v[46:47], v68 offset:0
	ds_read_b64_tr_b16 v[48:49], v68 offset:0x400
	ds_read_b64_tr_b16 v[50:51], v68 offset:0x800
	ds_read_b64_tr_b16 v[52:53], v68 offset:0xc00
	ds_read_b64_tr_b16 v[54:55], v68 offset:0x200
	ds_read_b64_tr_b16 v[56:57], v68 offset:0x600
	ds_read_b64_tr_b16 v[58:59], v68 offset:0xa00
	ds_read_b64_tr_b16 v[60:61], v68 offset:0xe00
	s_waitcnt lgkmcnt(0)
	s_nop 0
	v_permlane32_swap_b32_e32 v36, v38
	v_permlane32_swap_b32_e32 v37, v39
	v_permlane32_swap_b32_e32 v42, v44
	v_permlane32_swap_b32_e32 v43, v45
	v_mfma_f32_32x32x16_bf16 v[0:15], v[36:39], v[46:49], v[0:15]
	v_mfma_f32_32x32x16_bf16 v[16:31], v[36:39], v[54:57], v[16:31]
	v_mfma_f32_32x32x16_bf16 v[0:15], v[42:45], v[50:53], v[0:15]
	v_mfma_f32_32x32x16_bf16 v[16:31], v[42:45], v[58:61], v[16:31]
	v_cmp_lt_u32_e32 vcc, 31, v87
	s_and_saveexec_b64 s[4:5], vcc
	s_xor_b64 s[4:5], exec, s[4:5]
	s_ashr_i32 s11, s10, 31
	s_lshl_b64 s[6:7], s[10:11], 15
	s_ashr_i32 s11, s79, 31
	s_add_u32 s6, s6, s79
	s_addc_u32 s7, s7, s11
	s_or_saveexec_b64 s[4:5], s[4:5]
	s_waitcnt lgkmcnt(14)
	v_add_f32_e32 v35, v40, v41
	v_mov_b64_e32 v[32:33], s[6:7]
	s_xor_b64 exec, exec, s[4:5]
	s_cbranch_execz .LBB0_82
; __device__ __forceinline__ void dil_wave_item(const bf16* __restrict__ qkv, bf16* __restrict__ odil, float* __restrict__ lse,
;                               int pat, int g  , int head, char* wl  , const int W) {
;     ...
;   if (hi == 0) lse[((size_t)pat * T + tbase + (i0 + r32) * dil) * 8 + head] = mx + __log2f(ls);
	v_log_f32_e32 v32, v35
	s_ashr_i32 s11, s10, 31
	s_ashr_i32 s66, s79, 31
	s_lshl_b64 s[6:7], s[10:11], 15
	s_add_u32 s6, s6, s79
	s_addc_u32 s7, s7, s66
	v_ashrrev_i32_e32 v87, 31, v86
	v_add_f32_e32 v34, v34, v32
	v_lshl_add_u64 v[32:33], s[6:7], 0, v[86:87]
	v_lshlrev_b64 v[32:33], 5, v[32:33]
	v_lshl_add_u64 v[32:33], s[72:73], 0, v[32:33]
	global_store_dword v[32:33], v34, off
	v_mov_b64_e32 v[32:33], s[6:7]
	s_branch .LBB0_82

; __device__ __forceinline__ int v_st(int k, int c) { const int kk = (k & ~0xC) | ((k & 4) << 1) | ((k & 8) >> 1); return ((kk >> 3) * 4 + (c >> 5)) * 512 + ((kk & 7) * 32 + (c & 31)) * 2; }
; __device__ __forceinline__ int v_rd_base(int lane) { return ((lane & 3) << 3) | (((lane >> 2) & 3) << 6) | (((lane >> 4) & 1) << 5) | (((lane >> 5) & 1) << 8); }
; #define SLOAD(i, k0) do { sr_[i].vs0 = *reinterpret_cast<const bf16x8*>(&Vh[(size_t)((k0) + sr) * LDQ + sc]); sr_[i].vs1 = *reinterpret_cast<const bf16x8*>(&Vh[(size_t)((k0) + 32 + sr) * LDQ + sc]); \
;     sr_[i].ks0 = *reinterpret_cast<const bf16x8*>(&Kh[(size_t)((k0) + sr) * LDQ + sc]); sr_[i].ks1 = *reinterpret_cast<const bf16x8*>(&Kh[(size_t)((k0) + 32 + sr) * LDQ + sc]); } while (0)
; template <bool SAFE>
; __device__ __forceinline__ void diff_core(const bf16* __restrict__ Kh, const bf16* __restrict__ Vh, const int NT, const bf16x8* qr, char* lds,
;                                           const int wid, const int lane_unused, f32x16* o, f32x16& lacc, float& l_reg) {
;     ...
;   const int sr = tid >> 4, sc = (tid & 15) * 8, vst0 = v_st(sr, sc), vst1 = v_st(32 + sr, sc);
;   const int vb0 = (int)(uintptr_t)V_lds + v_rd_base(lane);
;   const int cb0 = map * 64;
;   const int rk = (r32 & ~0xC) | ((r32 & 4) << 1) | ((r32 & 8) >> 1);
;   Stg sr_[1];
;     ...
;   f32x16 p0, p1; bf16x8 pa0, pa1, pa2, pa3;
;   u32x4 one_ = {0x3F803F80u, 0x3F803F80u, 0x3F803F80u, 0x3F803F80u}; asm volatile("" : "+v"(one_));
;   const bf16x8 ones = *reinterpret_cast<const bf16x8*>(&one_);
;   float ps = 0.f; f32x16 cinit = {};
;     ...
;   const int kw0 = KSWZ(sr, sc * 2), kw1 = KSWZ(32 + sr, sc * 2);
;   SLOAD(0, 0); asm volatile("s_waitcnt vmcnt(0)" ::: "memory"); SWRITE(0, 0);
;   SLOAD(0, 64); asm volatile("s_waitcnt vmcnt(0)" ::: "memory"); SWRITE(1, 0); __syncthreads();
;   SLOAD(0, 128);
;   FIXUP(K_lds, true);
; __device__ __forceinline__ void diff_attn_item(const bf16* __restrict__ qkv, bf16* __restrict__ mix, const float* __restrict__ dg,
;                                int tok0  , int key0  , int seq, int head, float lam, float oscale, const int W) {
;     ...
;   const bf16* Qw = qkv + (size_t)(tok0 + pair * 32 + r32) * LDQ + head * 128 + map * 64 + hi * 8;
; #pragma unroll
;   for (int d0 = 0; d0 < 4; ++d0) qr[d0] = *reinterpret_cast<const bf16x8*>(Qw + d0 * 16);
.LBB0_102:
	v_mbcnt_lo_u32_b32 v0, -1, 0
	v_mbcnt_hi_u32_b32 v0, -1, v0
	s_add_i32 s6, s91, s61
	v_and_b32_e32 v199, 31, v0
	v_add_u32_e32 v1, s6, v199
	v_mad_i64_i32 v[2:3], s[6:7], v1, s80, v[192:193]
	s_lshl_b32 s12, s8, 8
	v_bfe_u32 v198, v0, 5, 1
	v_lshl_add_u64 v[2:3], v[2:3], 0, s[12:13]
	s_lshl_b32 s6, s64, 1
	s_mov_b32 s7, s13
	v_lshl_add_u64 v[2:3], v[2:3], 0, s[6:7]
	v_lshlrev_b32_e32 v194, 4, v198
	s_lshl_b64 s[4:5], s[4:5], 1
	v_lshl_add_u64 v[2:3], v[2:3], 0, v[194:195]
	s_add_u32 s4, s36, s4
	global_load_dwordx4 v[132:135], v[2:3], off
	global_load_dwordx4 v[136:139], v[2:3], off offset:32
	global_load_dwordx4 v[140:143], v[2:3], off offset:64
	global_load_dwordx4 v[144:147], v[2:3], off offset:96
	s_addc_u32 s5, s37, s5
	v_mbcnt_lo_u32_b32 v2, -1, 0
	v_mbcnt_hi_u32_b32 v2, -1, v2
	s_add_u32 s10, s4, s12
	v_add_u32_e32 v3, s60, v2
	v_ashrrev_i32_e32 v201, 4, v3
	v_lshlrev_b32_e32 v1, 3, v2
	s_addc_u32 s11, s5, 0
	v_and_b32_e32 v36, 0x78, v1
	v_mad_i64_i32 v[4:5], s[4:5], v201, s79, 0
	v_add_u32_e32 v202, 32, v201
	v_or_b32_e32 v4, v4, v36
	v_lshl_add_u64 v[8:9], v[4:5], 1, s[10:11]
	v_mad_i64_i32 v[4:5], s[4:5], v202, s79, 0
	v_add_u32_e32 v20, 64, v201
	v_add_u32_e32 v24, 0x60, v201
	v_or_b32_e32 v4, v4, v36
	v_mad_i64_i32 v[20:21], s[4:5], v20, s79, 0
	v_mad_i64_i32 v[24:25], s[4:5], v24, s79, 0
	v_and_b32_e32 v248, 15, v2
	v_bfe_u32 v249, v2, 4, 1
	v_cmp_eq_u32_e32 vcc, v248, v249
	s_nop 1
	v_cndmask_b32_e32 v148, 0, v128, vcc
	v_mov_b32_e32 v149, v148
	v_mov_b32_e32 v150, v148
	v_mov_b32_e32 v151, v148
	v_lshl_add_u64 v[16:17], v[4:5], 1, s[10:11]
	v_or_b32_e32 v20, v20, v36
	v_or_b32_e32 v24, v24, v36
	global_load_dwordx4 v[4:7], v[8:9], off offset:2048
	s_nop 0
	global_load_dwordx4 v[8:11], v[8:9], off offset:1024
	s_nop 0
	global_load_dwordx4 v[12:15], v[16:17], off offset:2048
	s_nop 0
	global_load_dwordx4 v[16:19], v[16:17], off offset:1024
	v_lshl_add_u64 v[28:29], v[20:21], 1, s[10:11]
	v_lshl_add_u64 v[32:33], v[24:25], 1, s[10:11]
	global_load_dwordx4 v[20:23], v[28:29], off offset:2048
	global_load_dwordx4 v[24:27], v[32:33], off offset:2048
	s_nop 0
	global_load_dwordx4 v[28:31], v[28:29], off offset:1024
	s_nop 0
	global_load_dwordx4 v[32:35], v[32:33], off offset:1024
	v_and_b32_e32 v38, 0xfffff0, v201
	v_lshlrev_b32_e32 v39, 1, v201
	v_lshrrev_b32_e32 v40, 1, v201
	v_and_b32_e32 v41, 3, v201
	v_and_or_b32 v38, v39, 8, v38
	v_and_or_b32 v39, v40, 4, v41
	v_and_b32_e32 v41, 0xfffff0, v202
	v_lshlrev_b32_e32 v43, 1, v202
	v_bfe_u32 v37, v1, 5, 2
	v_lshrrev_b32_e32 v38, 1, v38
	v_and_or_b32 v41, v43, 8, v41
	v_lshlrev_b32_e32 v194, 1, v36
	v_or_b32_e32 v38, v38, v37
	v_lshrrev_b32_e32 v41, 1, v41
	v_and_b32_e32 v3, 0xf0, v3
	v_lshlrev_b32_e32 v42, 8, v201
	v_and_b32_e32 v40, 48, v194
	v_lshlrev_b32_e32 v39, 6, v39
	v_lshlrev_b32_e32 v38, 9, v38
	v_or_b32_e32 v37, v41, v37
	v_bitop3_b32 v203, v194, v42, v3 bitop3:0xde
	v_lshlrev_b32_e32 v42, 8, v202
	v_or3_b32 v205, v38, v39, v40
	v_lshlrev_b32_e32 v37, 9, v37
	v_bitop3_b32 v204, v42, v194, v3 bitop3:0xf6
	v_add_u32_e32 v3, 0, v203
	v_or3_b32 v206, v37, v39, v40
	v_add_u32_e32 v37, 0, v205
	v_add_u32_e32 v43, 0, v204
	v_add_u32_e32 v38, 0, v206
	v_add_u32_e32 v42, s81, v203
	s_waitcnt vmcnt(7)
	ds_write_b128 v37, v[4:7]
	s_waitcnt vmcnt(5)
	ds_write_b128 v38, v[12:15]
	ds_write_b128 v3, v[8:11] offset:49152
	s_waitcnt vmcnt(4)
	ds_write_b128 v43, v[16:19] offset:49152
	v_add_u32_e32 v3, s81, v204
	s_waitcnt vmcnt(0)
	s_waitcnt vmcnt(3)
	ds_write_b128 v37, v[20:23] offset:16384
	s_waitcnt vmcnt(2)
	ds_write_b128 v38, v[24:27] offset:16384
	s_waitcnt vmcnt(1)
	ds_write_b128 v42, v[28:31]
	s_waitcnt vmcnt(0)
	ds_write_b128 v3, v[32:35]
	v_add_u32_e32 v3, 0x80, v201
	v_mad_i64_i32 v[4:5], s[4:5], v3, s79, 0
	v_add_u32_e32 v3, 0xa0, v201
	v_or_b32_e32 v4, v4, v36
	v_mad_i64_i32 v[6:7], s[4:5], v3, s79, 0
	v_lshl_add_u64 v[4:5], v[4:5], 1, s[10:11]
	v_or_b32_e32 v6, v6, v36
	s_waitcnt lgkmcnt(0)
	s_barrier
	v_lshl_add_u64 v[6:7], v[6:7], 1, s[10:11]
	global_load_dwordx4 v[166:169], v[4:5], off offset:1024
	global_load_dwordx4 v[162:165], v[6:7], off offset:1024
	global_load_dwordx4 v[156:159], v[4:5], off offset:2048
	global_load_dwordx4 v[152:155], v[6:7], off offset:2048
	v_lshlrev_b32_e32 v4, 1, v2
	v_lshrrev_b32_e32 v6, 1, v2
	v_and_b32_e32 v3, 19, v2
	v_and_b32_e32 v5, 8, v4
	v_and_b32_e32 v6, 4, v6
	v_or3_b32 v5, v5, v3, v6
	v_ashrrev_i32_e32 v3, 1, v2
	v_and_b32_e32 v3, -16, v3
	v_lshlrev_b32_e32 v15, 8, v5
	v_lshlrev_b32_e32 v5, 4, v5
	v_add_u32_e32 v14, s63, v3
	v_and_b32_e32 v5, 0xf0, v5
	v_xad_u32 v207, v5, v14, v15
	v_add_u32_e32 v10, 0, v207
	ds_read_b128 v[6:9], v10 offset:49152
	ds_read_b128 v[10:13], v10 offset:57344
	s_waitcnt lgkmcnt(1)
	v_mfma_f32_32x32x16_bf16 v[16:31], v[6:9], v[132:135], 0
	v_add_u32_e32 v6, 32, v14
	v_xad_u32 v208, v5, v6, v15
	v_add_u32_e32 v32, 0, v208
	ds_read_b128 v[6:9], v32 offset:49152
	ds_read_b128 v[48:51], v32 offset:57344
	s_waitcnt lgkmcnt(1)
	v_mfma_f32_32x32x16_bf16 v[16:31], v[6:9], v[136:139], v[16:31]
	v_add_u32_e32 v6, 64, v14
	v_xad_u32 v209, v5, v6, v15
	v_add_u32_e32 v32, 0, v209
	ds_read_b128 v[6:9], v32 offset:49152
	ds_read_b128 v[52:55], v32 offset:57344
	s_waitcnt lgkmcnt(1)
	v_mfma_f32_32x32x16_bf16 v[16:31], v[6:9], v[140:143], v[16:31]
	v_add_u32_e32 v6, 0x60, v14
	v_xad_u32 v210, v5, v6, v15
	v_add_u32_e32 v5, 0, v210
	ds_read_b128 v[6:9], v5 offset:49152
	ds_read_b128 v[56:59], v5 offset:57344
	s_waitcnt lgkmcnt(1)
	v_mfma_f32_32x32x16_bf16 v[16:31], v[6:9], v[144:147], v[16:31]
	v_mfma_f32_32x32x16_bf16 v[32:47], v[10:13], v[132:135], 0
	s_nop 10
	v_max_f32_e32 v5, v17, v17
	v_max_f32_e32 v6, v16, v16
	v_max_f32_e32 v5, v6, v5
	v_max3_f32 v5, v5, v18, v19
	v_max3_f32 v5, v5, v20, v21
	v_max3_f32 v5, v5, v22, v23
	v_max3_f32 v5, v5, v24, v25
	v_mfma_f32_32x32x16_bf16 v[32:47], v[48:51], v[136:139], v[32:47]
	v_max3_f32 v5, v5, v26, v27
	v_max3_f32 v5, v5, v28, v29
	v_max3_f32 v5, v5, v30, v31
	v_cmp_gt_u32_e32 vcc, 32, v2
	v_mfma_f32_32x32x16_bf16 v[32:47], v[52:55], v[140:143], v[32:47]
	s_waitcnt lgkmcnt(0)
	v_mfma_f32_32x32x16_bf16 v[32:47], v[56:59], v[144:147], v[32:47]
	s_nop 11
	v_max3_f32 v5, v5, v32, v33
	v_max3_f32 v5, v5, v34, v35
	v_max3_f32 v5, v5, v36, v37
	v_max3_f32 v5, v5, v38, v39
	v_max3_f32 v5, v5, v40, v41
	v_max3_f32 v5, v5, v42, v43
	v_max3_f32 v5, v5, v44, v45
	v_max3_f32 v5, v5, v46, v47
	v_mov_b32_e32 v6, v5
	s_nop 1
	v_permlane32_swap_b32_e32 v5, v6
	v_max3_f32 v48, v5, v6, s84
	s_and_saveexec_b64 s[4:5], vcc
	s_cbranch_execz .LBB0_104
	v_sub_f32_e32 v5, 0xf149f2ca, v48
	v_exp_f32_e32 v5, v5
	v_lshl_add_u32 v6, v2, 2, s62
	ds_write_b32 v6, v5 offset:128
; #define SLOAD(i, k0) do { sr_[i].vs0 = *reinterpret_cast<const bf16x8*>(&Vh[(size_t)((k0) + sr) * LDQ + sc]); sr_[i].vs1 = *reinterpret_cast<const bf16x8*>(&Vh[(size_t)((k0) + 32 + sr) * LDQ + sc]); \
;     sr_[i].ks0 = *reinterpret_cast<const bf16x8*>(&Kh[(size_t)((k0) + sr) * LDQ + sc]); sr_[i].ks1 = *reinterpret_cast<const bf16x8*>(&Kh[(size_t)((k0) + 32 + sr) * LDQ + sc]); } while (0)
; #define SWRITE(b, i) do { *(bf16x8*)((char*)V_lds + (b) * SHM_V + vst0) = sr_[i].vs0;          \
;     *(bf16x8*)((char*)V_lds + (b) * SHM_V + vst1) = sr_[i].vs1; int kc = sc * 2;               \
;     *(bf16x8*)((char*)K_lds + (b) * SHM_K + KSWZ(sr, kc)) = sr_[i].ks0;                       \
;     *(bf16x8*)((char*)K_lds + (b) * SHM_K + KSWZ(32 + sr, kc)) = sr_[i].ks1; } while (0)
; template <bool SAFE>
; __device__ __forceinline__ void diff_core(const bf16* __restrict__ Kh, const bf16* __restrict__ Vh, const int NT, const bf16x8* qr, char* lds,
;                                           const int wid, const int lane_unused, f32x16* o, f32x16& lacc, float& l_reg) {
;     ...
;   const int kw0 = KSWZ(sr, sc * 2), kw1 = KSWZ(32 + sr, sc * 2);
;   SLOAD(0, 0); asm volatile("s_waitcnt vmcnt(0)" ::: "memory"); SWRITE(0, 0);
;   SLOAD(0, 64); asm volatile("s_waitcnt vmcnt(0)" ::: "memory"); SWRITE(1, 0); __syncthreads();
;   SLOAD(0, 128);
;   FIXUP(K_lds, true);
;   int bc = 1, bp = 0, bn = 2;
.LBB0_104:
	s_or_b64 exec, exec, s[4:5]
	v_and_b32_e32 v200, 63, v0
	v_lshlrev_b32_e32 v0, 4, v2
	v_and_b32_e32 v0, 0xc0, v0
	v_and_or_b32 v0, v1, 24, v0
	v_and_b32_e32 v2, 32, v4
	v_and_b32_e32 v1, 0x100, v1
	s_waitcnt lgkmcnt(0)
	v_add_u32_e32 v9, s62, v3
	v_or3_b32 v8, v0, v2, v1
	ds_read_b128 v[0:3], v9 offset:192
	ds_read_b128 v[4:7], v9 offset:224
	ds_read_b128 v[50:53], v9 offset:128
	ds_read_b128 v[54:57], v9 offset:160
	v_sub_f32_e32 v16, v16, v48
	v_sub_f32_e32 v17, v17, v48
	v_sub_f32_e32 v18, v18, v48
	v_sub_f32_e32 v19, v19, v48
	v_sub_f32_e32 v20, v20, v48
	v_sub_f32_e32 v21, v21, v48
	v_sub_f32_e32 v22, v22, v48
	v_sub_f32_e32 v23, v23, v48
	v_sub_f32_e32 v24, v24, v48
	v_sub_f32_e32 v25, v25, v48
	v_sub_f32_e32 v26, v26, v48
	v_sub_f32_e32 v27, v27, v48
	v_sub_f32_e32 v28, v28, v48
	v_sub_f32_e32 v29, v29, v48
	v_sub_f32_e32 v30, v30, v48
	v_sub_f32_e32 v31, v31, v48
	v_sub_f32_e32 v32, v32, v48
	v_sub_f32_e32 v33, v33, v48
	v_sub_f32_e32 v34, v34, v48
	v_sub_f32_e32 v35, v35, v48
	v_sub_f32_e32 v36, v36, v48
	v_sub_f32_e32 v37, v37, v48
	v_sub_f32_e32 v38, v38, v48
	v_sub_f32_e32 v39, v39, v48
	v_sub_f32_e32 v40, v40, v48
	v_sub_f32_e32 v41, v41, v48
	v_sub_f32_e32 v42, v42, v48
	v_sub_f32_e32 v43, v43, v48
	v_sub_f32_e32 v44, v44, v48
	v_sub_f32_e32 v45, v45, v48
	v_sub_f32_e32 v46, v46, v48
	v_sub_f32_e32 v47, v47, v48
	v_exp_f32_e32 v16, v16
	v_exp_f32_e32 v17, v17
	v_exp_f32_e32 v18, v18
	v_exp_f32_e32 v19, v19
	v_exp_f32_e32 v20, v20
	v_exp_f32_e32 v21, v21
	v_exp_f32_e32 v22, v22
	v_exp_f32_e32 v23, v23
	v_exp_f32_e32 v24, v24
	v_exp_f32_e32 v25, v25
	v_exp_f32_e32 v26, v26
	v_exp_f32_e32 v27, v27
	v_exp_f32_e32 v28, v28
	v_exp_f32_e32 v29, v29
	v_exp_f32_e32 v30, v30
	v_exp_f32_e32 v31, v31
	v_exp_f32_e32 v32, v32
	v_exp_f32_e32 v33, v33
	v_exp_f32_e32 v34, v34
	v_exp_f32_e32 v35, v35
	v_exp_f32_e32 v36, v36
	v_exp_f32_e32 v37, v37
	v_exp_f32_e32 v38, v38
	v_exp_f32_e32 v39, v39
	v_exp_f32_e32 v40, v40
	v_exp_f32_e32 v41, v41
	v_exp_f32_e32 v42, v42
	v_exp_f32_e32 v43, v43
	v_exp_f32_e32 v44, v44
	v_exp_f32_e32 v45, v45
	v_exp_f32_e32 v46, v46
	v_exp_f32_e32 v47, v47
	s_lshl_b32 s12, s8, 7
	s_cmp_lg_u32 0, -1
	s_cselect_b32 s5, 0, 0
	s_waitcnt lgkmcnt(2)
	v_pk_mul_f32 v[14:15], v[6:7], 0 op_sel_hi:[1,0]
	v_xor_b32_e32 v80, 0x80000000, v48
	v_add_u32_e32 v211, s5, v8
	v_pk_mul_f32 v[10:11], v[2:3], 0 op_sel_hi:[1,0]
	s_waitcnt lgkmcnt(0)
	v_pk_mul_f32 v[6:7], v[56:57], 0 op_sel_hi:[1,0]
	v_pk_mul_f32 v[2:3], v[52:53], 0 op_sel_hi:[1,0]
	v_pk_mul_f32 v[12:13], v[4:5], 0 op_sel_hi:[1,0]
	v_pk_mul_f32 v[8:9], v[0:1], 0 op_sel_hi:[1,0]
	v_pk_mul_f32 v[4:5], v[54:55], 0 op_sel_hi:[1,0]
	v_pk_mul_f32 v[0:1], v[50:51], 0 op_sel_hi:[1,0]
	v_cvt_pk_bf16_f32 v160, v16, v17
	v_cvt_pk_bf16_f32 v161, v18, v19
	v_cvt_pk_bf16_f32 v182, v20, v21
	v_cvt_pk_bf16_f32 v183, v22, v23
	v_cvt_pk_bf16_f32 v170, v24, v25
	v_cvt_pk_bf16_f32 v171, v26, v27
	v_cvt_pk_bf16_f32 v186, v28, v29
	v_cvt_pk_bf16_f32 v187, v30, v31
	v_cvt_pk_bf16_f32 v180, v32, v33
	v_cvt_pk_bf16_f32 v181, v34, v35
	v_cvt_pk_bf16_f32 v178, v36, v37
	v_cvt_pk_bf16_f32 v179, v38, v39
	v_cvt_pk_bf16_f32 v188, v40, v41
	v_cvt_pk_bf16_f32 v189, v42, v43
	v_cvt_pk_bf16_f32 v174, v44, v45
	v_cvt_pk_bf16_f32 v175, v46, v47
	v_mov_b32_e32 v64, 0
	v_mov_b64_e32 v[46:47], v[14:15]
	v_mov_b64_e32 v[62:63], v[14:15]
	v_mov_b64_e32 v[30:31], v[14:15]
	v_mov_b32_e32 v81, v80
	v_mov_b32_e32 v82, v80
	v_mov_b32_e32 v83, v80
	v_mov_b32_e32 v84, v80
	v_mov_b32_e32 v85, v80
	v_mov_b32_e32 v86, v80
	v_mov_b32_e32 v87, v80
	v_mov_b32_e32 v88, v80
	v_mov_b32_e32 v89, v80
	v_mov_b32_e32 v90, v80
	v_mov_b32_e32 v91, v80
	v_mov_b32_e32 v92, v80
	v_mov_b32_e32 v93, v80
	v_mov_b32_e32 v94, v80
	v_mov_b32_e32 v95, v80
	s_mov_b32 s4, 0
	s_mov_b32 s5, 1
	v_lshl_add_u64 v[190:191], s[10:11], 0, v[194:195]
	v_mad_u32_u24 v247, v201, s80, v194
	s_add_i32 s93, s92, -1
	s_mov_b32 s9, 2
	v_mov_b64_e32 v[44:45], v[12:13]
	v_mov_b64_e32 v[42:43], v[10:11]
	v_mov_b64_e32 v[40:41], v[8:9]
	v_mov_b64_e32 v[38:39], v[6:7]
	v_mov_b64_e32 v[36:37], v[4:5]
	v_mov_b64_e32 v[34:35], v[2:3]
	v_mov_b64_e32 v[32:33], v[0:1]
	v_mov_b64_e32 v[60:61], v[12:13]
	v_mov_b64_e32 v[58:59], v[10:11]
	v_mov_b64_e32 v[56:57], v[8:9]
	v_mov_b64_e32 v[54:55], v[6:7]
	v_mov_b64_e32 v[52:53], v[4:5]
	v_mov_b64_e32 v[50:51], v[2:3]
	v_mov_b64_e32 v[48:49], v[0:1]
	v_mov_b64_e32 v[28:29], v[12:13]
	v_mov_b64_e32 v[26:27], v[10:11]
	v_mov_b64_e32 v[24:25], v[8:9]
	v_mov_b64_e32 v[22:23], v[6:7]
	v_mov_b64_e32 v[20:21], v[4:5]
	v_mov_b64_e32 v[18:19], v[2:3]
	v_mov_b64_e32 v[16:17], v[0:1]
	s_mov_b32 s6, 1
	v_mov_b32_e32 v65, v64
	v_mov_b32_e32 v66, v64
	v_mov_b32_e32 v67, v64
	v_mov_b32_e32 v68, v64
	v_mov_b32_e32 v69, v64
	v_mov_b32_e32 v70, v64
	v_mov_b32_e32 v71, v64
	v_mov_b32_e32 v72, v64
	v_mov_b32_e32 v73, v64
	v_mov_b32_e32 v74, v64
	v_mov_b32_e32 v75, v64
	v_mov_b32_e32 v76, v64
	v_mov_b32_e32 v77, v64
	v_mov_b32_e32 v78, v64
	v_mov_b32_e32 v79, v64
; template <int KS, bool SAFE> __device__ __forceinline__ void fused_ks(f32x16* o, f32x16& lacc, int vb, const VFrag& cur, VFrag& nxt, f32x16& p0, f32x16& p1, float& ps, ...
;   if constexpr (KS < 3) { vfrag_issue<KS + 1>(nxt, vb); asm volatile("s_waitcnt lgkmcnt(8)" ::: "memory"); }
;   else asm volatile("s_waitcnt lgkmcnt(0)" ::: "memory");
;   const bf16x8 pa = (KS == 0) ? pa0 : (KS == 1) ? pa1 : (KS == 2) ? pa2 : pa3;
;   SBAR();
;   o[0] = MFMA32(pa, PKV(cur.l0, cur.h0), o[0]); SBAR(); sm1_chunk<KS * 4 + 0>(p0, p1); if constexpr (KS > 0) SM2_UNIT(2 * KS - 1); SBAR();
;   o[1] = MFMA32(pa, PKV(cur.l1, cur.h1), o[1]); SBAR(); sm1_chunk<KS * 4 + 1>(p0, p1);
;   if (dow) {
;     if constexpr (KS == 0) { asm volatile("s_waitcnt vmcnt(0)" ::: "memory"); *reinterpret_cast<bf16x8*>(sd.k0) = st.ks0; }
;     else if constexpr (KS == 1) *reinterpret_cast<bf16x8*>(sd.k1) = st.ks1;
;     else if constexpr (KS == 2) *reinterpret_cast<bf16x8*>(sd.v0) = st.vs0;
;     else *reinterpret_cast<bf16x8*>(sd.v1) = st.vs1;
;   }
;   SBAR();
;   o[2] = MFMA32(pa, PKV(cur.l2, cur.h2), o[2]); SBAR(); sm1_chunk<KS * 4 + 2>(p0, p1); SM2_UNIT(2 * KS); SBAR();
;   o[3] = MFMA32(pa, PKV(cur.l3, cur.h3), o[3]); SBAR(); sm1_chunk<KS * 4 + 3>(p0, p1); SBAR();
;   if constexpr (!SAFE) { lacc = MFMA32(pa, ones, lacc); SBAR(); }
; }
; template <bool SAFE> ...
;   bf16x8 kb[8];
; #pragma unroll
;   for (int d0 = 0; d0 < 4; ++d0) { const int cb = (cb0 + d0 * 16 + hi * 8) * 2;
;     kb[2 * d0] = *reinterpret_cast<const bf16x8*>((const char*)Ks + KSWZ(r32, cb));
;     kb[2 * d0 + 1] = *reinterpret_cast<const bf16x8*>((const char*)Ks + KSWZ(32 + r32, cb)); }
;   VFrag fa, fb;
;   vfrag_issue<0>(fa, vb);
;   p0 = MFMA32(kb[0], qr[0], cinit); p1 = MFMA32(kb[1], qr[0], cinit);
; #pragma unroll
;   for (int d0 = 1; d0 < 4; ++d0) { p0 = MFMA32(kb[2 * d0], qr[d0], p0); p1 = MFMA32(kb[2 * d0 + 1], qr[d0], p1); }
;   SBAR();
;   unsigned a0, a1, b0, b1; ps = 0.f;
;   fused_ks<0, SAFE>(o, lacc, vb, fa, fb, p0, p1, ps, a0, a1, b0, b1, pa0, pa1, pa2, pa3, st, sd, dow, ones);
;   fused_ks<1, SAFE>(o, lacc, vb, fb, fa, p0, p1, ps, a0, a1, b0, b1, pa0, pa1, pa2, pa3, st, sd, dow, ones);
;   fused_ks<2, SAFE>(o, lacc, vb, fa, fb, p0, p1, ps, a0, a1, b0, b1, pa0, pa1, pa2, pa3, st, sd, dow, ones);
;   fused_ks<3, SAFE>(o, lacc, vb, fb, fa, p0, p1, ps, a0, a1, b0, b1, pa0, pa1, pa2, pa3, st, sd, dow, ones);
.LBB0_105:
	s_lshl_b32 s7, s6, 14
	s_add_i32 s66, s7, 0
	v_add_u32_e32 v100, s66, v207
	ds_read_b128 v[96:99], v100 offset:49152
	ds_read_b128 v[212:215], v100 offset:57344
	s_add_i32 s98, s5, 2
	s_min_i32 s98, s98, s93
	s_mul_i32 s98, s98, 0x60000
	s_add_u32 s98, s10, s98
	s_addc_u32 s99, s11, 0
	s_add_u32 s100, s98, 0x30000
	s_addc_u32 s101, s99, 0
	v_add_u32_e32 v172, s66, v208
	v_add_u32_e32 v173, s66, v209
	v_mov_b32_e32 v176, v180
	s_waitcnt lgkmcnt(1)
	v_mfma_f32_32x32x16_bf16 v[112:127], v[96:99], v[132:135], v[80:95]
	v_mov_b32_e32 v180, v160
	v_add_u32_e32 v160, s66, v210
	v_lshl_add_u32 v194, s4, 14, v211
	s_mov_b32 s8, s9
	s_lshl_b32 s9, s9, 14
	s_add_i32 s9, s9, 0
	v_mov_b32_e32 v184, v170
	s_waitcnt lgkmcnt(0)
	v_mfma_f32_32x32x16_bf16 v[96:111], v[212:215], v[132:135], v[80:95]
	ds_read_b128 v[212:215], v172 offset:49152
	ds_read_b128 v[216:219], v172 offset:57344
	v_mov_b32_e32 v177, v181
	v_mov_b32_e32 v172, v188
	v_mov_b32_e32 v181, v161
	v_add_u32_e32 v188, s9, v205
	v_add_u32_e32 v161, s9, v203
	v_add_u32_e32 v170, s9, v204
	s_waitcnt lgkmcnt(1)
	v_mfma_f32_32x32x16_bf16 v[112:127], v[212:215], v[136:139], v[112:127]
	ds_read_b128 v[212:215], v173 offset:49152
	v_mov_b32_e32 v185, v171
	s_waitcnt lgkmcnt(1)
	v_mfma_f32_32x32x16_bf16 v[96:111], v[216:219], v[136:139], v[96:111]
	ds_read_b128 v[216:219], v173 offset:57344
	v_mov_b32_e32 v173, v189
	v_add_u32_e32 v189, s9, v206
	s_waitcnt lgkmcnt(1)
	v_mfma_f32_32x32x16_bf16 v[112:127], v[212:215], v[140:143], v[112:127]
	ds_read_b128 v[212:215], v160 offset:49152
	s_waitcnt lgkmcnt(1)
	v_mfma_f32_32x32x16_bf16 v[96:111], v[216:219], v[140:143], v[96:111]
	ds_read_b128 v[216:219], v160 offset:57344
	ds_read_b64_tr_b16 v[220:221], v194 offset:0
	ds_read_b64_tr_b16 v[222:223], v194 offset:0x800
	s_waitcnt lgkmcnt(1)
	v_mfma_f32_32x32x16_bf16 v[112:127], v[212:215], v[144:147], v[112:127]
	ds_read_b64_tr_b16 v[212:213], v194 offset:0x200
	ds_read_b64_tr_b16 v[214:215], v194 offset:0xa00
	ds_read_b64_tr_b16 v[224:225], v194 offset:0x400
	ds_read_b64_tr_b16 v[226:227], v194 offset:0xc00
	ds_read_b64_tr_b16 v[228:229], v194 offset:0x600
	ds_read_b64_tr_b16 v[230:231], v194 offset:0xe00
	s_waitcnt lgkmcnt(0)
	v_mfma_f32_32x32x16_bf16 v[96:111], v[216:219], v[144:147], v[96:111]
	ds_read_b64_tr_b16 v[216:217], v194 offset:0x1000
	ds_read_b64_tr_b16 v[218:219], v194 offset:0x1800
	ds_read_b64_tr_b16 v[232:233], v194 offset:0x1200
	ds_read_b64_tr_b16 v[234:235], v194 offset:0x1a00
	ds_read_b64_tr_b16 v[236:237], v194 offset:0x1400
	ds_read_b64_tr_b16 v[238:239], v194 offset:0x1c00
	ds_read_b64_tr_b16 v[240:241], v194 offset:0x1600
	ds_read_b64_tr_b16 v[242:243], v194 offset:0x1e00
	s_waitcnt lgkmcnt(8)
	v_mfma_f32_32x32x16_bf16 v[48:63], v[180:183], v[220:223], v[48:63]
	s_nop 0
	v_exp_f32_e32 v112, v112
	v_exp_f32_e32 v113, v113
	v_mfma_f32_32x32x16_bf16 v[32:47], v[180:183], v[212:215], v[32:47]
	v_exp_f32_e32 v114, v114
	v_exp_f32_e32 v115, v115
	s_waitcnt vmcnt(3)
	ds_write_b128 v161, v[166:169] offset:49152
	global_load_dwordx4 v[166:169], v247, s[98:99] offset:1024
	v_mfma_f32_32x32x16_bf16 v[0:15], v[180:183], v[224:227], v[0:15]
	v_exp_f32_e32 v171, v116
	v_cvt_pk_bf16_f32 v160, v112, v113
	v_cvt_pk_bf16_f32 v161, v114, v115
	v_exp_f32_e32 v220, v117
	v_mfma_f32_32x32x16_bf16 v[16:31], v[180:183], v[228:231], v[16:31]
	v_exp_f32_e32 v221, v118
	v_exp_f32_e32 v222, v119
	v_mfma_f32_16x16x32_bf16 v[64:67], v[180:183], v[148:151], v[64:67]
	ds_read_b64_tr_b16 v[112:113], v194 offset:0x2000
	ds_read_b64_tr_b16 v[114:115], v194 offset:0x2800
	ds_read_b64_tr_b16 v[116:117], v194 offset:0x2200
	ds_read_b64_tr_b16 v[118:119], v194 offset:0x2a00
	ds_read_b64_tr_b16 v[248:249], v194 offset:0x2400
	ds_read_b64_tr_b16 v[250:251], v194 offset:0x2c00
	ds_read_b64_tr_b16 v[212:213], v194 offset:0x2600
	ds_read_b64_tr_b16 v[214:215], v194 offset:0x2e00
	s_waitcnt lgkmcnt(8)
	v_mfma_f32_32x32x16_bf16 v[48:63], v[184:187], v[216:219], v[48:63]
	v_cvt_pk_bf16_f32 v182, v171, v220
	v_cvt_pk_bf16_f32 v183, v221, v222
	v_exp_f32_e32 v120, v120
	v_exp_f32_e32 v121, v121
	v_mfma_f32_32x32x16_bf16 v[32:47], v[184:187], v[232:235], v[32:47]
	v_exp_f32_e32 v122, v122
	v_exp_f32_e32 v123, v123
	s_waitcnt vmcnt(3)
	ds_write_b128 v170, v[162:165] offset:49152
	global_load_dwordx4 v[162:165], v247, s[100:101] offset:1024
	v_mfma_f32_32x32x16_bf16 v[0:15], v[184:187], v[236:239], v[0:15]
	v_exp_f32_e32 v180, v124
	v_exp_f32_e32 v181, v125
	v_cvt_pk_bf16_f32 v170, v120, v121
	v_cvt_pk_bf16_f32 v171, v122, v123
	v_mfma_f32_32x32x16_bf16 v[16:31], v[184:187], v[240:243], v[16:31]
	v_exp_f32_e32 v220, v126
	v_exp_f32_e32 v221, v127
	v_mfma_f32_16x16x32_bf16 v[64:67], v[184:187], v[148:151], v[64:67]
	ds_read_b64_tr_b16 v[120:121], v194 offset:0x3000
	ds_read_b64_tr_b16 v[122:123], v194 offset:0x3800
	ds_read_b64_tr_b16 v[124:125], v194 offset:0x3200
	ds_read_b64_tr_b16 v[126:127], v194 offset:0x3a00
	ds_read_b64_tr_b16 v[252:253], v194 offset:0x3400
	ds_read_b64_tr_b16 v[254:255], v194 offset:0x3c00
	ds_read_b64_tr_b16 v[216:217], v194 offset:0x3600
	ds_read_b64_tr_b16 v[218:219], v194 offset:0x3e00
	s_waitcnt lgkmcnt(8)
	v_mfma_f32_32x32x16_bf16 v[48:63], v[176:179], v[112:115], v[48:63]
	v_cvt_pk_bf16_f32 v186, v180, v181
	v_cvt_pk_bf16_f32 v187, v220, v221
	v_exp_f32_e32 v96, v96
	v_exp_f32_e32 v97, v97
	v_mfma_f32_32x32x16_bf16 v[32:47], v[176:179], v[116:119], v[32:47]
	v_exp_f32_e32 v98, v98
	v_exp_f32_e32 v99, v99
	s_waitcnt vmcnt(3)
	ds_write_b128 v188, v[156:159]
	global_load_dwordx4 v[156:159], v247, s[98:99] offset:2048
	v_mfma_f32_32x32x16_bf16 v[0:15], v[176:179], v[248:251], v[0:15]
	v_cvt_pk_bf16_f32 v180, v96, v97
	v_cvt_pk_bf16_f32 v181, v98, v99
	v_exp_f32_e32 v100, v100
	v_exp_f32_e32 v101, v101
	v_mfma_f32_32x32x16_bf16 v[16:31], v[176:179], v[212:215], v[16:31]
	v_exp_f32_e32 v96, v102
	v_exp_f32_e32 v97, v103
	v_mfma_f32_16x16x32_bf16 v[64:67], v[176:179], v[148:151], v[64:67]
	s_waitcnt lgkmcnt(0)
	v_mfma_f32_32x32x16_bf16 v[48:63], v[172:175], v[120:123], v[48:63]
	v_cvt_pk_bf16_f32 v178, v100, v101
	v_cvt_pk_bf16_f32 v179, v96, v97
	v_exp_f32_e32 v98, v104
	v_exp_f32_e32 v99, v105
	v_mfma_f32_32x32x16_bf16 v[32:47], v[172:175], v[124:127], v[32:47]
	v_exp_f32_e32 v96, v106
	v_exp_f32_e32 v97, v107
	s_waitcnt vmcnt(3)
	ds_write_b128 v189, v[152:155]
	global_load_dwordx4 v[152:155], v247, s[100:101] offset:2048
	v_mfma_f32_32x32x16_bf16 v[0:15], v[172:175], v[252:255], v[0:15]
	v_cvt_pk_bf16_f32 v188, v98, v99
	v_cvt_pk_bf16_f32 v189, v96, v97
	v_exp_f32_e32 v100, v108
	v_exp_f32_e32 v101, v109
	v_mfma_f32_32x32x16_bf16 v[16:31], v[172:175], v[216:219], v[16:31]
	v_exp_f32_e32 v96, v110
	v_exp_f32_e32 v97, v111
	v_mfma_f32_16x16x32_bf16 v[64:67], v[172:175], v[148:151], v[64:67]
	v_cvt_pk_bf16_f32 v174, v100, v101
	v_cvt_pk_bf16_f32 v175, v96, v97
	s_waitcnt lgkmcnt(0)
	s_barrier
; #define SBAR() __builtin_amdgcn_sched_barrier(0)
; #define MFMA32(a, b, c) __builtin_amdgcn_mfma_f32_32x32x16_bf16(a, b, c, 0, 0, 0)
; #define SLOAD(i, k0) do { sr_[i].vs0 = *reinterpret_cast<const bf16x8*>(&Vh[(size_t)((k0) + sr) * LDQ + sc]); sr_[i].vs1 = *reinterpret_cast<const bf16x8*>(&Vh[(size_t)((k0) + 32 + sr) * LDQ + sc]); \
;     sr_[i].ks0 = *reinterpret_cast<const bf16x8*>(&Kh[(size_t)((k0) + sr) * LDQ + sc]); sr_[i].ks1 = *reinterpret_cast<const bf16x8*>(&Kh[(size_t)((k0) + 32 + sr) * LDQ + sc]); } while (0)
; template <bool SAFE>
; __device__ __forceinline__ void diff_core(const bf16* __restrict__ Kh, const bf16* __restrict__ Vh, const int NT, const bf16x8* qr, char* lds,
;                                           const int wid, const int lane_unused, f32x16* o, f32x16& lacc, float& l_reg) {
;     ...
;   for (int j = 1; j < NT; ++j) {
;     const bool dow = true;
;     const bf16* Kc = (const bf16*)((const char*)K_lds + bc * SHM_K);
;     StgDst sd;
;     sd.v0 = (char*)V_lds + bn * SHM_V + vst0; sd.v1 = (char*)V_lds + bn * SHM_V + vst1;
;     sd.k0 = (char*)K_lds + bn * SHM_K + kw0;  sd.k1 = (char*)K_lds + bn * SHM_K + kw1;
;     tile_step<SAFE>(o, lacc, Kc, vb0 + bp * SHM_V, qr, rk, hi, cb0, p0, p1, cinit, ps, pa0, pa1, pa2, pa3, sr_[0], sd, dow, ones);
;     SLOAD(0, min(j + 2, NT - 1) * 64);
;     SBAR();
;     if constexpr (SAFE) FIXUP(Kc, false);
;     asm volatile("s_waitcnt lgkmcnt(0)" ::: "memory"); __builtin_amdgcn_s_barrier(); asm volatile("" ::: "memory");
;     const int t_ = bp; bp = bc; bc = bn; bn = t_;
;   }
;   pv_d0(o, vb0 + bp * SHM_V, pa0, pa1, pa2, pa3);
;   if constexpr (!SAFE) {
;     lacc = MFMA32(pa0, ones, lacc); lacc = MFMA32(pa1, ones, lacc); lacc = MFMA32(pa2, ones, lacc); lacc = MFMA32(pa3, ones, lacc); }
; __device__ __forceinline__ void diff_attn_item(const bf16* __restrict__ qkv, bf16* __restrict__ mix, const float* __restrict__ dg,
;                                int tok0  , int key0  , int seq, int head, float lam, float oscale, const int W) {
;     ...
;     bool bad = (FORCE_SAFE != 0);
; #pragma unroll
;     for (int r = 0; r < 16; ++r) bad = bad || !(lacc[r] < 1.0e30f);
;     if (lane == 0) flag_l[wid] = __any(bad) ? 1 : 0;
	s_add_i32 s5, s5, 1
	s_mov_b32 s9, s4
	s_mov_b32 s4, s6
	s_cmp_lg_u32 s92, s5
	s_mov_b32 s6, s8
	s_cbranch_scc1 .LBB0_105
	s_waitcnt vmcnt(0)
	v_add_u32_e32 v168, s7, v211
	ds_read_b64_tr_b16 v[80:81], v168 offset:0
	ds_read_b64_tr_b16 v[82:83], v168 offset:0x800
	ds_read_b64_tr_b16 v[84:85], v168 offset:0x1000
	ds_read_b64_tr_b16 v[86:87], v168 offset:0x1800
	ds_read_b64_tr_b16 v[88:89], v168 offset:0x2000
	ds_read_b64_tr_b16 v[90:91], v168 offset:0x2800
	ds_read_b64_tr_b16 v[92:93], v168 offset:0x3000
	ds_read_b64_tr_b16 v[94:95], v168 offset:0x3800
	s_waitcnt lgkmcnt(0)
	s_waitcnt vmcnt(0)
	v_mov_b32_e32 v162, v182
	v_mov_b32_e32 v163, v183
	v_mov_b32_e32 v172, v186
	v_mov_b32_e32 v173, v187
	v_mov_b32_e32 v182, v178
	v_mov_b32_e32 v183, v179
	v_mov_b32_e32 v190, v174
	v_mov_b32_e32 v191, v175
	ds_read_b64_tr_b16 v[96:97], v168 offset:0x200
	ds_read_b64_tr_b16 v[98:99], v168 offset:0xa00
	ds_read_b64_tr_b16 v[100:101], v168 offset:0x1200
	ds_read_b64_tr_b16 v[102:103], v168 offset:0x1a00
	ds_read_b64_tr_b16 v[104:105], v168 offset:0x2200
	ds_read_b64_tr_b16 v[106:107], v168 offset:0x2a00
	ds_read_b64_tr_b16 v[108:109], v168 offset:0x3200
	ds_read_b64_tr_b16 v[110:111], v168 offset:0x3a00
	s_waitcnt lgkmcnt(0)
	ds_read_b64_tr_b16 v[112:113], v168 offset:0x400
	ds_read_b64_tr_b16 v[114:115], v168 offset:0xc00
	ds_read_b64_tr_b16 v[116:117], v168 offset:0x1400
	ds_read_b64_tr_b16 v[118:119], v168 offset:0x1c00
	ds_read_b64_tr_b16 v[120:121], v168 offset:0x2400
	ds_read_b64_tr_b16 v[122:123], v168 offset:0x2c00
	ds_read_b64_tr_b16 v[124:125], v168 offset:0x3400
	ds_read_b64_tr_b16 v[126:127], v168 offset:0x3c00
	s_waitcnt lgkmcnt(0)
	ds_read_b64_tr_b16 v[152:153], v168 offset:0x600
	ds_read_b64_tr_b16 v[154:155], v168 offset:0xe00
	ds_read_b64_tr_b16 v[156:157], v168 offset:0x1600
	ds_read_b64_tr_b16 v[158:159], v168 offset:0x1e00
	ds_read_b64_tr_b16 v[164:165], v168 offset:0x2600
	ds_read_b64_tr_b16 v[166:167], v168 offset:0x2e00
	ds_read_b64_tr_b16 v[174:175], v168 offset:0x3600
	ds_read_b64_tr_b16 v[176:177], v168 offset:0x3e00
	s_waitcnt lgkmcnt(0)
	v_mfma_f32_16x16x32_bf16 v[64:67], v[160:163], v[148:151], v[64:67]
	v_cmp_eq_u32_e32 vcc, 0, v200
	v_mfma_f32_32x32x16_bf16 v[48:63], v[160:163], v[80:83], v[48:63]
	v_mfma_f32_32x32x16_bf16 v[32:47], v[160:163], v[96:99], v[32:47]
	v_mfma_f32_32x32x16_bf16 v[0:15], v[160:163], v[112:115], v[0:15]
	v_mfma_f32_32x32x16_bf16 v[16:31], v[160:163], v[152:155], v[16:31]
	v_mfma_f32_16x16x32_bf16 v[64:67], v[170:173], v[148:151], v[64:67]
	v_mfma_f32_32x32x16_bf16 v[48:63], v[170:173], v[84:87], v[48:63]
	v_mfma_f32_32x32x16_bf16 v[32:47], v[170:173], v[100:103], v[32:47]
	v_mfma_f32_32x32x16_bf16 v[0:15], v[170:173], v[116:119], v[0:15]
	v_mfma_f32_32x32x16_bf16 v[16:31], v[170:173], v[156:159], v[16:31]
	v_mfma_f32_16x16x32_bf16 v[64:67], v[180:183], v[148:151], v[64:67]
	v_mfma_f32_32x32x16_bf16 v[48:63], v[180:183], v[88:91], v[48:63]
	v_mfma_f32_32x32x16_bf16 v[32:47], v[180:183], v[104:107], v[32:47]
	v_mfma_f32_32x32x16_bf16 v[0:15], v[180:183], v[120:123], v[0:15]
	v_mfma_f32_32x32x16_bf16 v[16:31], v[180:183], v[164:167], v[16:31]
	v_mfma_f32_16x16x32_bf16 v[64:67], v[188:191], v[148:151], v[64:67]
	v_mfma_f32_32x32x16_bf16 v[48:63], v[188:191], v[92:95], v[48:63]
	v_mfma_f32_32x32x16_bf16 v[32:47], v[188:191], v[108:111], v[32:47]
	v_mfma_f32_32x32x16_bf16 v[0:15], v[188:191], v[124:127], v[0:15]
	v_mfma_f32_32x32x16_bf16 v[16:31], v[188:191], v[174:177], v[16:31]
	v_and_b32_e32 v248, 15, v200
	v_lshrrev_b32_e32 v249, 4, v200
	v_and_b32_e32 v250, 1, v200
	v_lshlrev_b32_e32 v249, 4, v249
	v_lshl_add_u32 v249, v250, 6, v249
	v_add_u32_e32 v249, s62, v249
	v_cmp_gt_u32_e64 s[98:99], 2, v248
	v_lshl_add_u32 v250, v198, 4, s62
	s_nop 7
	s_and_saveexec_b64 s[100:101], s[98:99]
	ds_write_b128 v249, v[64:67]
	s_mov_b64 exec, s[100:101]
	s_waitcnt lgkmcnt(0)
	ds_read_b128 v[64:67], v250
	ds_read_b128 v[68:71], v250 offset:32
	ds_read_b128 v[72:75], v250 offset:64
	ds_read_b128 v[76:79], v250 offset:96
	s_waitcnt lgkmcnt(0)
	s_and_saveexec_b64 s[6:7], vcc
	s_cbranch_execz .LBB0_108
	s_nop 5
	v_cmp_ngt_f32_e32 vcc, s85, v64
	v_cmp_ngt_f32_e64 s[4:5], s85, v65
	s_or_b64 s[4:5], vcc, s[4:5]
	v_cmp_ngt_f32_e32 vcc, s85, v66
	s_or_b64 s[4:5], s[4:5], vcc
	v_cmp_ngt_f32_e32 vcc, s85, v67
	s_or_b64 s[4:5], s[4:5], vcc
	v_cmp_ngt_f32_e32 vcc, s85, v68
	s_or_b64 s[4:5], s[4:5], vcc
	v_cmp_ngt_f32_e32 vcc, s85, v69
	s_or_b64 s[4:5], s[4:5], vcc
	v_cmp_ngt_f32_e32 vcc, s85, v70
	s_or_b64 s[4:5], s[4:5], vcc
	v_cmp_ngt_f32_e32 vcc, s85, v71
	s_or_b64 s[4:5], s[4:5], vcc
	v_cmp_ngt_f32_e32 vcc, s85, v72
	s_or_b64 s[4:5], s[4:5], vcc
	v_cmp_ngt_f32_e32 vcc, s85, v73
	s_or_b64 s[4:5], s[4:5], vcc
	v_cmp_ngt_f32_e32 vcc, s85, v74
	s_or_b64 s[4:5], s[4:5], vcc
	v_cmp_ngt_f32_e32 vcc, s85, v75
	s_or_b64 s[4:5], s[4:5], vcc
	v_cmp_ngt_f32_e32 vcc, s85, v76
	s_or_b64 s[4:5], s[4:5], vcc
	v_cmp_ngt_f32_e32 vcc, s85, v77
	s_or_b64 s[4:5], s[4:5], vcc
	v_cmp_ngt_f32_e32 vcc, s85, v78
	s_or_b64 s[4:5], s[4:5], vcc
	v_cmp_ngt_f32_e32 vcc, s85, v79
	s_or_b64 s[4:5], s[4:5], vcc
	v_cndmask_b32_e64 v80, 0, 1, s[4:5]
	v_cmp_ne_u32_e32 vcc, 0, v80
	s_cmp_lg_u64 vcc, 0
	s_cselect_b64 s[4:5], -1, 0
	v_cndmask_b32_e64 v80, 0, 1, s[4:5]
	v_readlane_b32 s4, v246, 17
	s_nop 1
	v_mov_b32_e32 v81, s4
	ds_write_b32 v81, v80

; __device__ __forceinline__ int v_st(int k, int c) { const int kk = (k & ~0xC) | ((k & 4) << 1) | ((k & 8) >> 1); return ((kk >> 3) * 4 + (c >> 5)) * 512 + ((kk & 7) * 32 + (c & 31)) * 2; }
; __device__ __forceinline__ int v_rd_base(int lane) { return ((lane & 3) << 3) | (((lane >> 2) & 3) << 6) | (((lane >> 4) & 1) << 5) | (((lane >> 5) & 1) << 8); }
; #define SLOAD(i, k0) do { sr_[i].vs0 = *reinterpret_cast<const bf16x8*>(&Vh[(size_t)((k0) + sr) * LDQ + sc]); sr_[i].vs1 = *reinterpret_cast<const bf16x8*>(&Vh[(size_t)((k0) + 32 + sr) * LDQ + sc]); \
;     sr_[i].ks0 = *reinterpret_cast<const bf16x8*>(&Kh[(size_t)((k0) + sr) * LDQ + sc]); sr_[i].ks1 = *reinterpret_cast<const bf16x8*>(&Kh[(size_t)((k0) + 32 + sr) * LDQ + sc]); } while (0)
; template <bool SAFE>
; __device__ __forceinline__ void diff_core(const bf16* __restrict__ Kh, const bf16* __restrict__ Vh, const int NT, const bf16x8* qr, char* lds,
;                                           const int wid, const int lane_unused, f32x16* o, f32x16& lacc, float& l_reg) {
;     ...
;   const int sr = tid >> 4, sc = (tid & 15) * 8, vst0 = v_st(sr, sc), vst1 = v_st(32 + sr, sc);
;   const int vb0 = (int)(uintptr_t)V_lds + v_rd_base(lane);
;   const int cb0 = map * 64;
;   const int rk = (r32 & ~0xC) | ((r32 & 4) << 1) | ((r32 & 8) >> 1);
;   Stg sr_[1];
;     ...
;   f32x16 p0, p1; bf16x8 pa0, pa1, pa2, pa3;
;   u32x4 one_ = {0x3F803F80u, 0x3F803F80u, 0x3F803F80u, 0x3F803F80u}; asm volatile("" : "+v"(one_));
;   const bf16x8 ones = *reinterpret_cast<const bf16x8*>(&one_);
;   float ps = 0.f; f32x16 cinit = {};
;     ...
;   const int kw0 = KSWZ(sr, sc * 2), kw1 = KSWZ(32 + sr, sc * 2);
;   SLOAD(0, 0); asm volatile("s_waitcnt vmcnt(0)" ::: "memory"); SWRITE(0, 0);
;   SLOAD(0, 64); asm volatile("s_waitcnt vmcnt(0)" ::: "memory"); SWRITE(1, 0); __syncthreads();
;   SLOAD(0, 128);
;   FIXUP(K_lds, true);
; __device__ __forceinline__ void diff_attn_item(const bf16* __restrict__ qkv, bf16* __restrict__ mix, const float* __restrict__ dg,
;                                int tok0  , int key0  , int seq, int head, float lam, float oscale, const int W) {
;     ...
;   const bf16* Qw = qkv + (size_t)(tok0 + pair * 32 + r32) * LDQ + head * 128 + map * 64 + hi * 8;
; #pragma unroll
;   for (int d0 = 0; d0 < 4; ++d0) qr[d0] = *reinterpret_cast<const bf16x8*>(Qw + d0 * 16);
.LBB0_313:
	v_mbcnt_lo_u32_b32 v0, -1, 0
	v_mbcnt_hi_u32_b32 v0, -1, v0
	s_add_i32 s8, s51, s61
	v_and_b32_e32 v199, 31, v0
	v_add_u32_e32 v1, s8, v199
	v_mad_i64_i32 v[2:3], s[8:9], v1, s41, v[192:193]
	s_lshl_b32 s20, s26, 8
	v_bfe_u32 v198, v0, 5, 1
	v_lshl_add_u64 v[2:3], v[2:3], 0, s[20:21]
	v_lshl_add_u64 v[2:3], v[2:3], 0, s[24:25]
	v_lshlrev_b32_e32 v194, 4, v198
	s_lshl_b64 s[6:7], s[6:7], 1
	v_lshl_add_u64 v[2:3], v[2:3], 0, v[194:195]
	s_add_u32 s6, s36, s6
	global_load_dwordx4 v[132:135], v[2:3], off
	global_load_dwordx4 v[136:139], v[2:3], off offset:32
	global_load_dwordx4 v[140:143], v[2:3], off offset:64
	global_load_dwordx4 v[144:147], v[2:3], off offset:96
	s_addc_u32 s7, s37, s7
	v_mbcnt_lo_u32_b32 v2, -1, 0
	v_mbcnt_hi_u32_b32 v2, -1, v2
	s_add_u32 s14, s6, s20
	v_add_u32_e32 v3, s60, v2
	v_ashrrev_i32_e32 v201, 4, v3
	v_lshlrev_b32_e32 v1, 3, v2
	s_addc_u32 s15, s7, 0
	v_and_b32_e32 v36, 0x78, v1
	v_mad_i64_i32 v[4:5], s[6:7], v201, s40, 0
	v_add_u32_e32 v202, 32, v201
	v_or_b32_e32 v4, v4, v36
	v_lshl_add_u64 v[8:9], v[4:5], 1, s[14:15]
	v_mad_i64_i32 v[4:5], s[6:7], v202, s40, 0
	v_or_b32_e32 v4, v4, v36
	v_and_b32_e32 v248, 15, v2
	v_bfe_u32 v249, v2, 4, 1
	v_cmp_eq_u32_e32 vcc, v248, v249
	s_nop 1
	v_cndmask_b32_e32 v148, 0, v128, vcc
	v_mov_b32_e32 v149, v148
	v_mov_b32_e32 v150, v148
	v_mov_b32_e32 v151, v148
	v_lshl_add_u64 v[16:17], v[4:5], 1, s[14:15]
	global_load_dwordx4 v[4:7], v[8:9], off offset:2048
	s_nop 0
	global_load_dwordx4 v[8:11], v[8:9], off offset:1024
	s_nop 0
	global_load_dwordx4 v[12:15], v[16:17], off offset:2048
	s_nop 0
	global_load_dwordx4 v[16:19], v[16:17], off offset:1024
	v_add_u32_e32 v20, 64, v201
	v_add_u32_e32 v24, 0x60, v201
	v_mad_i64_i32 v[20:21], s[6:7], v20, s40, 0
	v_mad_i64_i32 v[24:25], s[6:7], v24, s40, 0
	v_or_b32_e32 v20, v20, v36
	v_or_b32_e32 v24, v24, v36
	v_lshl_add_u64 v[28:29], v[20:21], 1, s[14:15]
	v_lshl_add_u64 v[32:33], v[24:25], 1, s[14:15]
	global_load_dwordx4 v[20:23], v[28:29], off offset:2048
	global_load_dwordx4 v[24:27], v[32:33], off offset:2048
	s_nop 0
	global_load_dwordx4 v[28:31], v[28:29], off offset:1024
	s_nop 0
	global_load_dwordx4 v[32:35], v[32:33], off offset:1024
	v_and_b32_e32 v38, 0xfffff0, v201
	v_lshlrev_b32_e32 v39, 1, v201
	v_lshrrev_b32_e32 v40, 1, v201
	v_and_b32_e32 v41, 3, v201
	v_and_or_b32 v38, v39, 8, v38
	v_and_or_b32 v39, v40, 4, v41
	v_and_b32_e32 v41, 0xfffff0, v202
	v_lshlrev_b32_e32 v43, 1, v202
	v_bfe_u32 v37, v1, 5, 2
	v_lshrrev_b32_e32 v38, 1, v38
	v_and_or_b32 v41, v43, 8, v41
	v_lshlrev_b32_e32 v194, 1, v36
	v_or_b32_e32 v38, v38, v37
	v_lshrrev_b32_e32 v41, 1, v41
	v_and_b32_e32 v3, 0xf0, v3
	v_lshlrev_b32_e32 v42, 8, v201
	v_and_b32_e32 v40, 48, v194
	v_lshlrev_b32_e32 v39, 6, v39
	v_lshlrev_b32_e32 v38, 9, v38
	v_or_b32_e32 v37, v41, v37
	v_bitop3_b32 v203, v194, v42, v3 bitop3:0xde
	v_lshlrev_b32_e32 v42, 8, v202
	v_or3_b32 v205, v38, v39, v40
	v_lshlrev_b32_e32 v37, 9, v37
	v_bitop3_b32 v204, v42, v194, v3 bitop3:0xf6
	v_add_u32_e32 v3, 0, v203
	v_or3_b32 v206, v37, v39, v40
	v_add_u32_e32 v37, 0, v205
	v_add_u32_e32 v43, 0, v204
	v_add_u32_e32 v38, 0, v206
	v_add_u32_e32 v42, s42, v203
	v_add_u32_e32 v44, s42, v204
	s_waitcnt vmcnt(7)
	ds_write_b128 v37, v[4:7]
	s_waitcnt vmcnt(5)
	ds_write_b128 v38, v[12:15]
	ds_write_b128 v3, v[8:11] offset:49152
	s_waitcnt vmcnt(4)
	ds_write_b128 v43, v[16:19] offset:49152
	v_add_u32_e32 v3, 0x80, v201
	v_mad_i64_i32 v[4:5], s[6:7], v3, s40, 0
	v_add_u32_e32 v3, 0xa0, v201
	v_or_b32_e32 v4, v4, v36
	v_mad_i64_i32 v[6:7], s[6:7], v3, s40, 0
	v_lshl_add_u64 v[4:5], v[4:5], 1, s[14:15]
	v_or_b32_e32 v6, v6, v36
	s_waitcnt vmcnt(0)
	s_waitcnt vmcnt(3)
	ds_write_b128 v37, v[20:23] offset:16384
	s_waitcnt vmcnt(2)
	ds_write_b128 v38, v[24:27] offset:16384
	s_waitcnt vmcnt(1)
	ds_write_b128 v42, v[28:31]
	s_waitcnt vmcnt(0)
	ds_write_b128 v44, v[32:35]
	s_waitcnt lgkmcnt(0)
	s_barrier
	v_lshl_add_u64 v[6:7], v[6:7], 1, s[14:15]
	global_load_dwordx4 v[166:169], v[4:5], off offset:1024
	global_load_dwordx4 v[162:165], v[6:7], off offset:1024
	global_load_dwordx4 v[156:159], v[4:5], off offset:2048
	global_load_dwordx4 v[152:155], v[6:7], off offset:2048
	v_lshlrev_b32_e32 v4, 1, v2
	v_lshrrev_b32_e32 v6, 1, v2
	v_and_b32_e32 v3, 19, v2
	v_and_b32_e32 v5, 8, v4
	v_and_b32_e32 v6, 4, v6
	v_or3_b32 v5, v5, v3, v6
	v_ashrrev_i32_e32 v3, 1, v2
	v_and_b32_e32 v3, -16, v3
	v_lshlrev_b32_e32 v15, 8, v5
	v_lshlrev_b32_e32 v5, 4, v5
	v_add_u32_e32 v14, s63, v3
	v_and_b32_e32 v5, 0xf0, v5
	v_xad_u32 v207, v5, v14, v15
	v_add_u32_e32 v10, 0, v207
	ds_read_b128 v[6:9], v10 offset:49152
	ds_read_b128 v[10:13], v10 offset:57344
	s_waitcnt lgkmcnt(1)
	v_mfma_f32_32x32x16_bf16 v[16:31], v[6:9], v[132:135], 0
	v_add_u32_e32 v6, 32, v14
	v_xad_u32 v208, v5, v6, v15
	v_add_u32_e32 v32, 0, v208
	ds_read_b128 v[6:9], v32 offset:49152
	ds_read_b128 v[48:51], v32 offset:57344
	s_waitcnt lgkmcnt(1)
	v_mfma_f32_32x32x16_bf16 v[16:31], v[6:9], v[136:139], v[16:31]
	v_add_u32_e32 v6, 64, v14
	v_xad_u32 v209, v5, v6, v15
	v_add_u32_e32 v32, 0, v209
	ds_read_b128 v[6:9], v32 offset:49152
	ds_read_b128 v[52:55], v32 offset:57344
	s_waitcnt lgkmcnt(1)
	v_mfma_f32_32x32x16_bf16 v[16:31], v[6:9], v[140:143], v[16:31]
	v_add_u32_e32 v6, 0x60, v14
	v_xad_u32 v210, v5, v6, v15
	v_add_u32_e32 v5, 0, v210
	ds_read_b128 v[6:9], v5 offset:49152
	ds_read_b128 v[56:59], v5 offset:57344
	s_waitcnt lgkmcnt(1)
	v_mfma_f32_32x32x16_bf16 v[16:31], v[6:9], v[144:147], v[16:31]
	v_mfma_f32_32x32x16_bf16 v[32:47], v[10:13], v[132:135], 0
	s_nop 10
	v_max_f32_e32 v5, v17, v17
	v_max_f32_e32 v6, v16, v16
	v_max_f32_e32 v5, v6, v5
	v_max3_f32 v5, v5, v18, v19
	v_max3_f32 v5, v5, v20, v21
	v_max3_f32 v5, v5, v22, v23
	v_max3_f32 v5, v5, v24, v25
	v_mfma_f32_32x32x16_bf16 v[32:47], v[48:51], v[136:139], v[32:47]
	v_max3_f32 v5, v5, v26, v27
	v_max3_f32 v5, v5, v28, v29
	v_max3_f32 v5, v5, v30, v31
	v_cmp_gt_u32_e32 vcc, 32, v2
	v_mfma_f32_32x32x16_bf16 v[32:47], v[52:55], v[140:143], v[32:47]
	s_waitcnt lgkmcnt(0)
	v_mfma_f32_32x32x16_bf16 v[32:47], v[56:59], v[144:147], v[32:47]
	s_nop 11
	v_max3_f32 v5, v5, v32, v33
	v_max3_f32 v5, v5, v34, v35
	v_max3_f32 v5, v5, v36, v37
	v_max3_f32 v5, v5, v38, v39
	v_max3_f32 v5, v5, v40, v41
	v_max3_f32 v5, v5, v42, v43
	v_max3_f32 v5, v5, v44, v45
	v_max3_f32 v5, v5, v46, v47
	v_mov_b32_e32 v6, v5
	s_nop 1
	v_permlane32_swap_b32_e32 v5, v6
	v_max3_f32 v48, v5, v6, s43
	s_and_saveexec_b64 s[6:7], vcc
	s_cbranch_execz .LBB0_315
	v_sub_f32_e32 v5, 0xf149f2ca, v48
	v_exp_f32_e32 v5, v5
	v_lshl_add_u32 v6, v2, 2, s62
	ds_write_b32 v6, v5 offset:128
; #define SLOAD(i, k0) do { sr_[i].vs0 = *reinterpret_cast<const bf16x8*>(&Vh[(size_t)((k0) + sr) * LDQ + sc]); sr_[i].vs1 = *reinterpret_cast<const bf16x8*>(&Vh[(size_t)((k0) + 32 + sr) * LDQ + sc]); \
;     sr_[i].ks0 = *reinterpret_cast<const bf16x8*>(&Kh[(size_t)((k0) + sr) * LDQ + sc]); sr_[i].ks1 = *reinterpret_cast<const bf16x8*>(&Kh[(size_t)((k0) + 32 + sr) * LDQ + sc]); } while (0)
; #define SWRITE(b, i) do { *(bf16x8*)((char*)V_lds + (b) * SHM_V + vst0) = sr_[i].vs0;          \
;     *(bf16x8*)((char*)V_lds + (b) * SHM_V + vst1) = sr_[i].vs1; int kc = sc * 2;               \
;     *(bf16x8*)((char*)K_lds + (b) * SHM_K + KSWZ(sr, kc)) = sr_[i].ks0;                       \
;     *(bf16x8*)((char*)K_lds + (b) * SHM_K + KSWZ(32 + sr, kc)) = sr_[i].ks1; } while (0)
; template <bool SAFE>
; __device__ __forceinline__ void diff_core(const bf16* __restrict__ Kh, const bf16* __restrict__ Vh, const int NT, const bf16x8* qr, char* lds,
;                                           const int wid, const int lane_unused, f32x16* o, f32x16& lacc, float& l_reg) {
;     ...
;   const int kw0 = KSWZ(sr, sc * 2), kw1 = KSWZ(32 + sr, sc * 2);
;   SLOAD(0, 0); asm volatile("s_waitcnt vmcnt(0)" ::: "memory"); SWRITE(0, 0);
;   SLOAD(0, 64); asm volatile("s_waitcnt vmcnt(0)" ::: "memory"); SWRITE(1, 0); __syncthreads();
;   SLOAD(0, 128);
;   FIXUP(K_lds, true);
;   int bc = 1, bp = 0, bn = 2;
.LBB0_315:
	s_or_b64 exec, exec, s[6:7]
	v_and_b32_e32 v200, 63, v0
	v_lshlrev_b32_e32 v0, 4, v2
	v_and_b32_e32 v0, 0xc0, v0
	v_and_or_b32 v0, v1, 24, v0
	v_and_b32_e32 v2, 32, v4
	v_and_b32_e32 v1, 0x100, v1
	s_waitcnt lgkmcnt(0)
	v_add_u32_e32 v9, s62, v3
	v_or3_b32 v8, v0, v2, v1
	ds_read_b128 v[0:3], v9 offset:192
	ds_read_b128 v[4:7], v9 offset:224
	ds_read_b128 v[50:53], v9 offset:128
	ds_read_b128 v[54:57], v9 offset:160
	v_sub_f32_e32 v16, v16, v48
	v_sub_f32_e32 v17, v17, v48
	v_sub_f32_e32 v18, v18, v48
	v_sub_f32_e32 v19, v19, v48
	v_sub_f32_e32 v20, v20, v48
	v_sub_f32_e32 v21, v21, v48
	v_sub_f32_e32 v22, v22, v48
	v_sub_f32_e32 v23, v23, v48
	v_sub_f32_e32 v24, v24, v48
	v_sub_f32_e32 v25, v25, v48
	v_sub_f32_e32 v26, v26, v48
	v_sub_f32_e32 v27, v27, v48
	v_sub_f32_e32 v28, v28, v48
	v_sub_f32_e32 v29, v29, v48
	v_sub_f32_e32 v30, v30, v48
	v_sub_f32_e32 v31, v31, v48
	v_sub_f32_e32 v32, v32, v48
	v_sub_f32_e32 v33, v33, v48
	v_sub_f32_e32 v34, v34, v48
	v_sub_f32_e32 v35, v35, v48
	v_sub_f32_e32 v36, v36, v48
	v_sub_f32_e32 v37, v37, v48
	v_sub_f32_e32 v38, v38, v48
	v_sub_f32_e32 v39, v39, v48
	v_sub_f32_e32 v40, v40, v48
	v_sub_f32_e32 v41, v41, v48
	v_sub_f32_e32 v42, v42, v48
	v_sub_f32_e32 v43, v43, v48
	v_sub_f32_e32 v44, v44, v48
	v_sub_f32_e32 v45, v45, v48
	v_sub_f32_e32 v46, v46, v48
	v_sub_f32_e32 v47, v47, v48
	v_exp_f32_e32 v16, v16
	v_exp_f32_e32 v17, v17
	v_exp_f32_e32 v18, v18
	v_exp_f32_e32 v19, v19
	v_exp_f32_e32 v20, v20
	v_exp_f32_e32 v21, v21
	v_exp_f32_e32 v22, v22
	v_exp_f32_e32 v23, v23
	v_exp_f32_e32 v24, v24
	v_exp_f32_e32 v25, v25
	v_exp_f32_e32 v26, v26
	v_exp_f32_e32 v27, v27
	v_exp_f32_e32 v28, v28
	v_exp_f32_e32 v29, v29
	v_exp_f32_e32 v30, v30
	v_exp_f32_e32 v31, v31
	v_exp_f32_e32 v32, v32
	v_exp_f32_e32 v33, v33
	v_exp_f32_e32 v34, v34
	v_exp_f32_e32 v35, v35
	v_exp_f32_e32 v36, v36
	v_exp_f32_e32 v37, v37
	v_exp_f32_e32 v38, v38
	v_exp_f32_e32 v39, v39
	v_exp_f32_e32 v40, v40
	v_exp_f32_e32 v41, v41
	v_exp_f32_e32 v42, v42
	v_exp_f32_e32 v43, v43
	v_exp_f32_e32 v44, v44
	v_exp_f32_e32 v45, v45
	v_exp_f32_e32 v46, v46
	v_exp_f32_e32 v47, v47
	s_lshl_b32 s20, s26, 7
	s_cmp_lg_u32 0, -1
	s_cselect_b32 s7, 0, 0
	s_waitcnt lgkmcnt(2)
	v_pk_mul_f32 v[14:15], v[6:7], 0 op_sel_hi:[1,0]
	v_xor_b32_e32 v80, 0x80000000, v48
	v_add_u32_e32 v211, s7, v8
	v_pk_mul_f32 v[10:11], v[2:3], 0 op_sel_hi:[1,0]
	s_waitcnt lgkmcnt(0)
	v_pk_mul_f32 v[6:7], v[56:57], 0 op_sel_hi:[1,0]
	v_pk_mul_f32 v[2:3], v[52:53], 0 op_sel_hi:[1,0]
	v_pk_mul_f32 v[12:13], v[4:5], 0 op_sel_hi:[1,0]
	v_pk_mul_f32 v[8:9], v[0:1], 0 op_sel_hi:[1,0]
	v_pk_mul_f32 v[4:5], v[54:55], 0 op_sel_hi:[1,0]
	v_pk_mul_f32 v[0:1], v[50:51], 0 op_sel_hi:[1,0]
	v_cvt_pk_bf16_f32 v160, v16, v17
	v_cvt_pk_bf16_f32 v161, v18, v19
	v_cvt_pk_bf16_f32 v182, v20, v21
	v_cvt_pk_bf16_f32 v183, v22, v23
	v_cvt_pk_bf16_f32 v170, v24, v25
	v_cvt_pk_bf16_f32 v171, v26, v27
	v_cvt_pk_bf16_f32 v186, v28, v29
	v_cvt_pk_bf16_f32 v187, v30, v31
	v_cvt_pk_bf16_f32 v180, v32, v33
	v_cvt_pk_bf16_f32 v181, v34, v35
	v_cvt_pk_bf16_f32 v178, v36, v37
	v_cvt_pk_bf16_f32 v179, v38, v39
	v_cvt_pk_bf16_f32 v188, v40, v41
	v_cvt_pk_bf16_f32 v189, v42, v43
	v_cvt_pk_bf16_f32 v174, v44, v45
	v_cvt_pk_bf16_f32 v175, v46, v47
	v_mov_b32_e32 v64, 0
	v_mov_b64_e32 v[46:47], v[14:15]
	v_mov_b64_e32 v[62:63], v[14:15]
	v_mov_b64_e32 v[30:31], v[14:15]
	v_mov_b32_e32 v81, v80
	v_mov_b32_e32 v82, v80
	v_mov_b32_e32 v83, v80
	v_mov_b32_e32 v84, v80
	v_mov_b32_e32 v85, v80
	v_mov_b32_e32 v86, v80
	v_mov_b32_e32 v87, v80
	v_mov_b32_e32 v88, v80
	v_mov_b32_e32 v89, v80
	v_mov_b32_e32 v90, v80
	v_mov_b32_e32 v91, v80
	v_mov_b32_e32 v92, v80
	v_mov_b32_e32 v93, v80
	v_mov_b32_e32 v94, v80
	v_mov_b32_e32 v95, v80
	s_mov_b32 s6, 0
	s_mov_b32 s7, 1
	v_lshl_add_u64 v[190:191], s[14:15], 0, v[194:195]
	v_mad_u32_u24 v247, v201, s41, v194
	s_add_i32 s64, s55, -1
	s_mov_b32 s27, 2
	v_mov_b64_e32 v[44:45], v[12:13]
	v_mov_b64_e32 v[42:43], v[10:11]
	v_mov_b64_e32 v[40:41], v[8:9]
	v_mov_b64_e32 v[38:39], v[6:7]
	v_mov_b64_e32 v[36:37], v[4:5]
	v_mov_b64_e32 v[34:35], v[2:3]
	v_mov_b64_e32 v[32:33], v[0:1]
	v_mov_b64_e32 v[60:61], v[12:13]
	v_mov_b64_e32 v[58:59], v[10:11]
	v_mov_b64_e32 v[56:57], v[8:9]
	v_mov_b64_e32 v[54:55], v[6:7]
	v_mov_b64_e32 v[52:53], v[4:5]
	v_mov_b64_e32 v[50:51], v[2:3]
	v_mov_b64_e32 v[48:49], v[0:1]
	v_mov_b64_e32 v[28:29], v[12:13]
	v_mov_b64_e32 v[26:27], v[10:11]
	v_mov_b64_e32 v[24:25], v[8:9]
	v_mov_b64_e32 v[22:23], v[6:7]
	v_mov_b64_e32 v[20:21], v[4:5]
	v_mov_b64_e32 v[18:19], v[2:3]
	v_mov_b64_e32 v[16:17], v[0:1]
	s_mov_b32 s10, 1
	v_mov_b32_e32 v65, v64
	v_mov_b32_e32 v66, v64
	v_mov_b32_e32 v67, v64
	v_mov_b32_e32 v68, v64
	v_mov_b32_e32 v69, v64
	v_mov_b32_e32 v70, v64
	v_mov_b32_e32 v71, v64
	v_mov_b32_e32 v72, v64
	v_mov_b32_e32 v73, v64
	v_mov_b32_e32 v74, v64
	v_mov_b32_e32 v75, v64
	v_mov_b32_e32 v76, v64
	v_mov_b32_e32 v77, v64
	v_mov_b32_e32 v78, v64
	v_mov_b32_e32 v79, v64
; template <int KS, bool SAFE> __device__ __forceinline__ void fused_ks(f32x16* o, f32x16& lacc, int vb, const VFrag& cur, VFrag& nxt, f32x16& p0, f32x16& p1, float& ps, ...
;   if constexpr (KS < 3) { vfrag_issue<KS + 1>(nxt, vb); asm volatile("s_waitcnt lgkmcnt(8)" ::: "memory"); }
;   else asm volatile("s_waitcnt lgkmcnt(0)" ::: "memory");
;   const bf16x8 pa = (KS == 0) ? pa0 : (KS == 1) ? pa1 : (KS == 2) ? pa2 : pa3;
;   SBAR();
;   o[0] = MFMA32(pa, PKV(cur.l0, cur.h0), o[0]); SBAR(); sm1_chunk<KS * 4 + 0>(p0, p1); if constexpr (KS > 0) SM2_UNIT(2 * KS - 1); SBAR();
;   o[1] = MFMA32(pa, PKV(cur.l1, cur.h1), o[1]); SBAR(); sm1_chunk<KS * 4 + 1>(p0, p1);
;   if (dow) {
;     if constexpr (KS == 0) { asm volatile("s_waitcnt vmcnt(0)" ::: "memory"); *reinterpret_cast<bf16x8*>(sd.k0) = st.ks0; }
;     else if constexpr (KS == 1) *reinterpret_cast<bf16x8*>(sd.k1) = st.ks1;
;     else if constexpr (KS == 2) *reinterpret_cast<bf16x8*>(sd.v0) = st.vs0;
;     else *reinterpret_cast<bf16x8*>(sd.v1) = st.vs1;
;   }
;   SBAR();
;   o[2] = MFMA32(pa, PKV(cur.l2, cur.h2), o[2]); SBAR(); sm1_chunk<KS * 4 + 2>(p0, p1); SM2_UNIT(2 * KS); SBAR();
;   o[3] = MFMA32(pa, PKV(cur.l3, cur.h3), o[3]); SBAR(); sm1_chunk<KS * 4 + 3>(p0, p1); SBAR();
;   if constexpr (!SAFE) { lacc = MFMA32(pa, ones, lacc); SBAR(); }
; }
; template <bool SAFE> ...
;   bf16x8 kb[8];
; #pragma unroll
;   for (int d0 = 0; d0 < 4; ++d0) { const int cb = (cb0 + d0 * 16 + hi * 8) * 2;
;     kb[2 * d0] = *reinterpret_cast<const bf16x8*>((const char*)Ks + KSWZ(r32, cb));
;     kb[2 * d0 + 1] = *reinterpret_cast<const bf16x8*>((const char*)Ks + KSWZ(32 + r32, cb)); }
;   VFrag fa, fb;
;   vfrag_issue<0>(fa, vb);
;   p0 = MFMA32(kb[0], qr[0], cinit); p1 = MFMA32(kb[1], qr[0], cinit);
; #pragma unroll
;   for (int d0 = 1; d0 < 4; ++d0) { p0 = MFMA32(kb[2 * d0], qr[d0], p0); p1 = MFMA32(kb[2 * d0 + 1], qr[d0], p1); }
;   SBAR();
;   unsigned a0, a1, b0, b1; ps = 0.f;
;   fused_ks<0, SAFE>(o, lacc, vb, fa, fb, p0, p1, ps, a0, a1, b0, b1, pa0, pa1, pa2, pa3, st, sd, dow, ones);
;   fused_ks<1, SAFE>(o, lacc, vb, fb, fa, p0, p1, ps, a0, a1, b0, b1, pa0, pa1, pa2, pa3, st, sd, dow, ones);
;   fused_ks<2, SAFE>(o, lacc, vb, fa, fb, p0, p1, ps, a0, a1, b0, b1, pa0, pa1, pa2, pa3, st, sd, dow, ones);
;   fused_ks<3, SAFE>(o, lacc, vb, fb, fa, p0, p1, ps, a0, a1, b0, b1, pa0, pa1, pa2, pa3, st, sd, dow, ones);
.LBB0_316:
	s_lshl_b32 s11, s10, 14
	s_add_i32 s8, s11, 0
	v_add_u32_e32 v100, s8, v207
	ds_read_b128 v[96:99], v100 offset:49152
	ds_read_b128 v[212:215], v100 offset:57344
	s_add_i32 s98, s7, 2
	s_min_i32 s98, s98, s64
	s_mul_i32 s98, s98, 0x60000
	s_add_u32 s98, s14, s98
	s_addc_u32 s99, s15, 0
	s_add_u32 s100, s98, 0x30000
	s_addc_u32 s101, s99, 0
	v_add_u32_e32 v172, s8, v208
	v_add_u32_e32 v173, s8, v209
	v_mov_b32_e32 v176, v180
	s_waitcnt lgkmcnt(1)
	v_mfma_f32_32x32x16_bf16 v[112:127], v[96:99], v[132:135], v[80:95]
	v_mov_b32_e32 v180, v160
	v_add_u32_e32 v160, s8, v210
	v_lshl_add_u32 v194, s6, 14, v211
	s_lshl_b32 s9, s27, 14
	s_add_i32 s9, s9, 0
	v_mov_b32_e32 v184, v170
	v_mov_b32_e32 v177, v181
	s_waitcnt lgkmcnt(0)
	v_mfma_f32_32x32x16_bf16 v[96:111], v[212:215], v[132:135], v[80:95]
	ds_read_b128 v[212:215], v172 offset:49152
	ds_read_b128 v[216:219], v172 offset:57344
	v_mov_b32_e32 v172, v188
	v_mov_b32_e32 v181, v161
	v_add_u32_e32 v188, s9, v205
	v_add_u32_e32 v161, s9, v203
	v_add_u32_e32 v170, s9, v204
	s_mov_b32 s26, s27
	s_waitcnt lgkmcnt(1)
	v_mfma_f32_32x32x16_bf16 v[112:127], v[212:215], v[136:139], v[112:127]
	ds_read_b128 v[212:215], v173 offset:49152
	v_mov_b32_e32 v185, v171
	s_waitcnt lgkmcnt(1)
	v_mfma_f32_32x32x16_bf16 v[96:111], v[216:219], v[136:139], v[96:111]
	ds_read_b128 v[216:219], v173 offset:57344
	v_mov_b32_e32 v173, v189
	v_add_u32_e32 v189, s9, v206
	s_waitcnt lgkmcnt(1)
	v_mfma_f32_32x32x16_bf16 v[112:127], v[212:215], v[140:143], v[112:127]
	ds_read_b128 v[212:215], v160 offset:49152
	s_waitcnt lgkmcnt(1)
	v_mfma_f32_32x32x16_bf16 v[96:111], v[216:219], v[140:143], v[96:111]
	ds_read_b128 v[216:219], v160 offset:57344
	ds_read_b64_tr_b16 v[220:221], v194 offset:0
	ds_read_b64_tr_b16 v[222:223], v194 offset:0x800
	s_waitcnt lgkmcnt(1)
	v_mfma_f32_32x32x16_bf16 v[112:127], v[212:215], v[144:147], v[112:127]
	ds_read_b64_tr_b16 v[212:213], v194 offset:0x200
	ds_read_b64_tr_b16 v[214:215], v194 offset:0xa00
	ds_read_b64_tr_b16 v[224:225], v194 offset:0x400
	ds_read_b64_tr_b16 v[226:227], v194 offset:0xc00
	ds_read_b64_tr_b16 v[228:229], v194 offset:0x600
	ds_read_b64_tr_b16 v[230:231], v194 offset:0xe00
	s_waitcnt lgkmcnt(0)
	v_mfma_f32_32x32x16_bf16 v[96:111], v[216:219], v[144:147], v[96:111]
	ds_read_b64_tr_b16 v[216:217], v194 offset:0x1000
	ds_read_b64_tr_b16 v[218:219], v194 offset:0x1800
	ds_read_b64_tr_b16 v[232:233], v194 offset:0x1200
	ds_read_b64_tr_b16 v[234:235], v194 offset:0x1a00
	ds_read_b64_tr_b16 v[236:237], v194 offset:0x1400
	ds_read_b64_tr_b16 v[238:239], v194 offset:0x1c00
	ds_read_b64_tr_b16 v[240:241], v194 offset:0x1600
	ds_read_b64_tr_b16 v[242:243], v194 offset:0x1e00
	s_waitcnt lgkmcnt(8)
	v_mfma_f32_32x32x16_bf16 v[48:63], v[180:183], v[220:223], v[48:63]
	s_nop 0
	v_exp_f32_e32 v112, v112
	v_exp_f32_e32 v113, v113
	v_mfma_f32_32x32x16_bf16 v[32:47], v[180:183], v[212:215], v[32:47]
	v_exp_f32_e32 v114, v114
	v_exp_f32_e32 v115, v115
	s_waitcnt vmcnt(3)
	ds_write_b128 v161, v[166:169] offset:49152
	global_load_dwordx4 v[166:169], v247, s[98:99] offset:1024
	v_mfma_f32_32x32x16_bf16 v[0:15], v[180:183], v[224:227], v[0:15]
	v_exp_f32_e32 v171, v116
	v_cvt_pk_bf16_f32 v160, v112, v113
	v_cvt_pk_bf16_f32 v161, v114, v115
	v_exp_f32_e32 v220, v117
	v_mfma_f32_32x32x16_bf16 v[16:31], v[180:183], v[228:231], v[16:31]
	v_exp_f32_e32 v221, v118
	v_exp_f32_e32 v222, v119
	v_mfma_f32_16x16x32_bf16 v[64:67], v[180:183], v[148:151], v[64:67]
	ds_read_b64_tr_b16 v[112:113], v194 offset:0x2000
	ds_read_b64_tr_b16 v[114:115], v194 offset:0x2800
	ds_read_b64_tr_b16 v[116:117], v194 offset:0x2200
	ds_read_b64_tr_b16 v[118:119], v194 offset:0x2a00
	ds_read_b64_tr_b16 v[248:249], v194 offset:0x2400
	ds_read_b64_tr_b16 v[250:251], v194 offset:0x2c00
	ds_read_b64_tr_b16 v[212:213], v194 offset:0x2600
	ds_read_b64_tr_b16 v[214:215], v194 offset:0x2e00
	s_waitcnt lgkmcnt(8)
	v_mfma_f32_32x32x16_bf16 v[48:63], v[184:187], v[216:219], v[48:63]
	v_cvt_pk_bf16_f32 v182, v171, v220
	v_cvt_pk_bf16_f32 v183, v221, v222
	v_exp_f32_e32 v120, v120
	v_exp_f32_e32 v121, v121
	v_mfma_f32_32x32x16_bf16 v[32:47], v[184:187], v[232:235], v[32:47]
	v_exp_f32_e32 v122, v122
	v_exp_f32_e32 v123, v123
	s_waitcnt vmcnt(3)
	ds_write_b128 v170, v[162:165] offset:49152
	global_load_dwordx4 v[162:165], v247, s[100:101] offset:1024
	v_mfma_f32_32x32x16_bf16 v[0:15], v[184:187], v[236:239], v[0:15]
	v_exp_f32_e32 v180, v124
	v_exp_f32_e32 v181, v125
	v_cvt_pk_bf16_f32 v170, v120, v121
	v_cvt_pk_bf16_f32 v171, v122, v123
	v_mfma_f32_32x32x16_bf16 v[16:31], v[184:187], v[240:243], v[16:31]
	v_exp_f32_e32 v220, v126
	v_exp_f32_e32 v221, v127
	v_mfma_f32_16x16x32_bf16 v[64:67], v[184:187], v[148:151], v[64:67]
	ds_read_b64_tr_b16 v[120:121], v194 offset:0x3000
	ds_read_b64_tr_b16 v[122:123], v194 offset:0x3800
	ds_read_b64_tr_b16 v[124:125], v194 offset:0x3200
	ds_read_b64_tr_b16 v[126:127], v194 offset:0x3a00
	ds_read_b64_tr_b16 v[252:253], v194 offset:0x3400
	ds_read_b64_tr_b16 v[254:255], v194 offset:0x3c00
	ds_read_b64_tr_b16 v[216:217], v194 offset:0x3600
	ds_read_b64_tr_b16 v[218:219], v194 offset:0x3e00
	s_waitcnt lgkmcnt(8)
	v_mfma_f32_32x32x16_bf16 v[48:63], v[176:179], v[112:115], v[48:63]
	v_cvt_pk_bf16_f32 v186, v180, v181
	v_cvt_pk_bf16_f32 v187, v220, v221
	v_exp_f32_e32 v96, v96
	v_exp_f32_e32 v97, v97
	v_mfma_f32_32x32x16_bf16 v[32:47], v[176:179], v[116:119], v[32:47]
	v_exp_f32_e32 v98, v98
	v_exp_f32_e32 v99, v99
	s_waitcnt vmcnt(3)
	ds_write_b128 v188, v[156:159]
	global_load_dwordx4 v[156:159], v247, s[98:99] offset:2048
	v_mfma_f32_32x32x16_bf16 v[0:15], v[176:179], v[248:251], v[0:15]
	v_cvt_pk_bf16_f32 v180, v96, v97
	v_cvt_pk_bf16_f32 v181, v98, v99
	v_exp_f32_e32 v100, v100
	v_exp_f32_e32 v101, v101
	v_mfma_f32_32x32x16_bf16 v[16:31], v[176:179], v[212:215], v[16:31]
	v_exp_f32_e32 v96, v102
	v_exp_f32_e32 v97, v103
	v_mfma_f32_16x16x32_bf16 v[64:67], v[176:179], v[148:151], v[64:67]
	s_waitcnt lgkmcnt(0)
	v_mfma_f32_32x32x16_bf16 v[48:63], v[172:175], v[120:123], v[48:63]
	v_cvt_pk_bf16_f32 v178, v100, v101
	v_cvt_pk_bf16_f32 v179, v96, v97
	v_exp_f32_e32 v98, v104
	v_exp_f32_e32 v99, v105
	v_mfma_f32_32x32x16_bf16 v[32:47], v[172:175], v[124:127], v[32:47]
	v_exp_f32_e32 v96, v106
	v_exp_f32_e32 v97, v107
	s_waitcnt vmcnt(3)
	ds_write_b128 v189, v[152:155]
	global_load_dwordx4 v[152:155], v247, s[100:101] offset:2048
	v_mfma_f32_32x32x16_bf16 v[0:15], v[172:175], v[252:255], v[0:15]
	v_cvt_pk_bf16_f32 v188, v98, v99
	v_cvt_pk_bf16_f32 v189, v96, v97
	v_exp_f32_e32 v100, v108
	v_exp_f32_e32 v101, v109
	v_mfma_f32_32x32x16_bf16 v[16:31], v[172:175], v[216:219], v[16:31]
	v_exp_f32_e32 v96, v110
	v_exp_f32_e32 v97, v111
	v_mfma_f32_16x16x32_bf16 v[64:67], v[172:175], v[148:151], v[64:67]
	v_cvt_pk_bf16_f32 v174, v100, v101
	v_cvt_pk_bf16_f32 v175, v96, v97
	s_waitcnt lgkmcnt(0)
	s_barrier
; #define SBAR() __builtin_amdgcn_sched_barrier(0)
; #define MFMA32(a, b, c) __builtin_amdgcn_mfma_f32_32x32x16_bf16(a, b, c, 0, 0, 0)
; #define SLOAD(i, k0) do { sr_[i].vs0 = *reinterpret_cast<const bf16x8*>(&Vh[(size_t)((k0) + sr) * LDQ + sc]); sr_[i].vs1 = *reinterpret_cast<const bf16x8*>(&Vh[(size_t)((k0) + 32 + sr) * LDQ + sc]); \
;     sr_[i].ks0 = *reinterpret_cast<const bf16x8*>(&Kh[(size_t)((k0) + sr) * LDQ + sc]); sr_[i].ks1 = *reinterpret_cast<const bf16x8*>(&Kh[(size_t)((k0) + 32 + sr) * LDQ + sc]); } while (0)
; template <bool SAFE>
; __device__ __forceinline__ void diff_core(const bf16* __restrict__ Kh, const bf16* __restrict__ Vh, const int NT, const bf16x8* qr, char* lds,
;                                           const int wid, const int lane_unused, f32x16* o, f32x16& lacc, float& l_reg) {
;     ...
;   for (int j = 1; j < NT; ++j) {
;     const bool dow = true;
;     const bf16* Kc = (const bf16*)((const char*)K_lds + bc * SHM_K);
;     StgDst sd;
;     sd.v0 = (char*)V_lds + bn * SHM_V + vst0; sd.v1 = (char*)V_lds + bn * SHM_V + vst1;
;     sd.k0 = (char*)K_lds + bn * SHM_K + kw0;  sd.k1 = (char*)K_lds + bn * SHM_K + kw1;
;     tile_step<SAFE>(o, lacc, Kc, vb0 + bp * SHM_V, qr, rk, hi, cb0, p0, p1, cinit, ps, pa0, pa1, pa2, pa3, sr_[0], sd, dow, ones);
;     SLOAD(0, min(j + 2, NT - 1) * 64);
;     SBAR();
;     if constexpr (SAFE) FIXUP(Kc, false);
;     asm volatile("s_waitcnt lgkmcnt(0)" ::: "memory"); __builtin_amdgcn_s_barrier(); asm volatile("" ::: "memory");
;     const int t_ = bp; bp = bc; bc = bn; bn = t_;
;   }
;   pv_d0(o, vb0 + bp * SHM_V, pa0, pa1, pa2, pa3);
;   if constexpr (!SAFE) {
;     lacc = MFMA32(pa0, ones, lacc); lacc = MFMA32(pa1, ones, lacc); lacc = MFMA32(pa2, ones, lacc); lacc = MFMA32(pa3, ones, lacc); }
; __device__ __forceinline__ void diff_attn_item(const bf16* __restrict__ qkv, bf16* __restrict__ mix, const float* __restrict__ dg,
;                                int tok0  , int key0  , int seq, int head, float lam, float oscale, const int W) {
;     ...
;     bool bad = (FORCE_SAFE != 0);
; #pragma unroll
;     for (int r = 0; r < 16; ++r) bad = bad || !(lacc[r] < 1.0e30f);
;     if (lane == 0) flag_l[wid] = __any(bad) ? 1 : 0;
	s_add_i32 s7, s7, 1
	s_mov_b32 s27, s6
	s_mov_b32 s6, s10
	s_cmp_lg_u32 s55, s7
	s_mov_b32 s10, s26
	s_cbranch_scc1 .LBB0_316
	s_waitcnt vmcnt(0)
	v_add_u32_e32 v168, s11, v211
	ds_read_b64_tr_b16 v[80:81], v168 offset:0
	ds_read_b64_tr_b16 v[82:83], v168 offset:0x800
	ds_read_b64_tr_b16 v[84:85], v168 offset:0x1000
	ds_read_b64_tr_b16 v[86:87], v168 offset:0x1800
	ds_read_b64_tr_b16 v[88:89], v168 offset:0x2000
	ds_read_b64_tr_b16 v[90:91], v168 offset:0x2800
	ds_read_b64_tr_b16 v[92:93], v168 offset:0x3000
	ds_read_b64_tr_b16 v[94:95], v168 offset:0x3800
	s_waitcnt lgkmcnt(0)
	s_waitcnt vmcnt(0)
	v_mov_b32_e32 v162, v182
	v_mov_b32_e32 v163, v183
	v_mov_b32_e32 v172, v186
	v_mov_b32_e32 v173, v187
	v_mov_b32_e32 v182, v178
	v_mov_b32_e32 v183, v179
	v_mov_b32_e32 v190, v174
	v_mov_b32_e32 v191, v175
	ds_read_b64_tr_b16 v[96:97], v168 offset:0x200
	ds_read_b64_tr_b16 v[98:99], v168 offset:0xa00
	ds_read_b64_tr_b16 v[100:101], v168 offset:0x1200
	ds_read_b64_tr_b16 v[102:103], v168 offset:0x1a00
	ds_read_b64_tr_b16 v[104:105], v168 offset:0x2200
	ds_read_b64_tr_b16 v[106:107], v168 offset:0x2a00
	ds_read_b64_tr_b16 v[108:109], v168 offset:0x3200
	ds_read_b64_tr_b16 v[110:111], v168 offset:0x3a00
	s_waitcnt lgkmcnt(0)
	ds_read_b64_tr_b16 v[112:113], v168 offset:0x400
	ds_read_b64_tr_b16 v[114:115], v168 offset:0xc00
	ds_read_b64_tr_b16 v[116:117], v168 offset:0x1400
	ds_read_b64_tr_b16 v[118:119], v168 offset:0x1c00
	ds_read_b64_tr_b16 v[120:121], v168 offset:0x2400
	ds_read_b64_tr_b16 v[122:123], v168 offset:0x2c00
	ds_read_b64_tr_b16 v[124:125], v168 offset:0x3400
	ds_read_b64_tr_b16 v[126:127], v168 offset:0x3c00
	s_waitcnt lgkmcnt(0)
	ds_read_b64_tr_b16 v[152:153], v168 offset:0x600
	ds_read_b64_tr_b16 v[154:155], v168 offset:0xe00
	ds_read_b64_tr_b16 v[156:157], v168 offset:0x1600
	ds_read_b64_tr_b16 v[158:159], v168 offset:0x1e00
	ds_read_b64_tr_b16 v[164:165], v168 offset:0x2600
	ds_read_b64_tr_b16 v[166:167], v168 offset:0x2e00
	ds_read_b64_tr_b16 v[174:175], v168 offset:0x3600
	ds_read_b64_tr_b16 v[176:177], v168 offset:0x3e00
	s_waitcnt lgkmcnt(0)
	v_mfma_f32_16x16x32_bf16 v[64:67], v[160:163], v[148:151], v[64:67]
	v_cmp_eq_u32_e32 vcc, 0, v200
	v_mfma_f32_32x32x16_bf16 v[48:63], v[160:163], v[80:83], v[48:63]
	v_mfma_f32_32x32x16_bf16 v[32:47], v[160:163], v[96:99], v[32:47]
	v_mfma_f32_32x32x16_bf16 v[0:15], v[160:163], v[112:115], v[0:15]
	v_mfma_f32_32x32x16_bf16 v[16:31], v[160:163], v[152:155], v[16:31]
	v_mfma_f32_16x16x32_bf16 v[64:67], v[170:173], v[148:151], v[64:67]
	v_mfma_f32_32x32x16_bf16 v[48:63], v[170:173], v[84:87], v[48:63]
	v_mfma_f32_32x32x16_bf16 v[32:47], v[170:173], v[100:103], v[32:47]
	v_mfma_f32_32x32x16_bf16 v[0:15], v[170:173], v[116:119], v[0:15]
	v_mfma_f32_32x32x16_bf16 v[16:31], v[170:173], v[156:159], v[16:31]
	v_mfma_f32_16x16x32_bf16 v[64:67], v[180:183], v[148:151], v[64:67]
	v_mfma_f32_32x32x16_bf16 v[48:63], v[180:183], v[88:91], v[48:63]
	v_mfma_f32_32x32x16_bf16 v[32:47], v[180:183], v[104:107], v[32:47]
	v_mfma_f32_32x32x16_bf16 v[0:15], v[180:183], v[120:123], v[0:15]
	v_mfma_f32_32x32x16_bf16 v[16:31], v[180:183], v[164:167], v[16:31]
	v_mfma_f32_16x16x32_bf16 v[64:67], v[188:191], v[148:151], v[64:67]
	v_mfma_f32_32x32x16_bf16 v[48:63], v[188:191], v[92:95], v[48:63]
	v_mfma_f32_32x32x16_bf16 v[32:47], v[188:191], v[108:111], v[32:47]
	v_mfma_f32_32x32x16_bf16 v[0:15], v[188:191], v[124:127], v[0:15]
	v_mfma_f32_32x32x16_bf16 v[16:31], v[188:191], v[174:177], v[16:31]
	v_and_b32_e32 v248, 15, v200
	v_lshrrev_b32_e32 v249, 4, v200
	v_and_b32_e32 v250, 1, v200
	v_lshlrev_b32_e32 v249, 4, v249
	v_lshl_add_u32 v249, v250, 6, v249
	v_add_u32_e32 v249, s62, v249
	v_cmp_gt_u32_e64 s[98:99], 2, v248
	v_lshl_add_u32 v250, v198, 4, s62
	s_nop 7
	s_and_saveexec_b64 s[100:101], s[98:99]
	ds_write_b128 v249, v[64:67]
	s_mov_b64 exec, s[100:101]
	s_waitcnt lgkmcnt(0)
	ds_read_b128 v[64:67], v250
	ds_read_b128 v[68:71], v250 offset:32
	ds_read_b128 v[72:75], v250 offset:64
	ds_read_b128 v[76:79], v250 offset:96
	s_waitcnt lgkmcnt(0)
	s_and_saveexec_b64 s[10:11], vcc
	s_cbranch_execz .LBB0_319
	s_nop 5
	v_cmp_ngt_f32_e32 vcc, s44, v64
	v_cmp_ngt_f32_e64 s[6:7], s44, v65
	s_or_b64 s[6:7], vcc, s[6:7]
	v_cmp_ngt_f32_e32 vcc, s44, v66
	s_or_b64 s[6:7], s[6:7], vcc
	v_cmp_ngt_f32_e32 vcc, s44, v67
	s_or_b64 s[6:7], s[6:7], vcc
	v_cmp_ngt_f32_e32 vcc, s44, v68
	s_or_b64 s[6:7], s[6:7], vcc
	v_cmp_ngt_f32_e32 vcc, s44, v69
	s_or_b64 s[6:7], s[6:7], vcc
	v_cmp_ngt_f32_e32 vcc, s44, v70
	s_or_b64 s[6:7], s[6:7], vcc
	v_cmp_ngt_f32_e32 vcc, s44, v71
	s_or_b64 s[6:7], s[6:7], vcc
	v_cmp_ngt_f32_e32 vcc, s44, v72
	s_or_b64 s[6:7], s[6:7], vcc
	v_cmp_ngt_f32_e32 vcc, s44, v73
	s_or_b64 s[6:7], s[6:7], vcc
	v_cmp_ngt_f32_e32 vcc, s44, v74
	s_or_b64 s[6:7], s[6:7], vcc
	v_cmp_ngt_f32_e32 vcc, s44, v75
	s_or_b64 s[6:7], s[6:7], vcc
	v_cmp_ngt_f32_e32 vcc, s44, v76
	s_or_b64 s[6:7], s[6:7], vcc
	v_cmp_ngt_f32_e32 vcc, s44, v77
	s_or_b64 s[6:7], s[6:7], vcc
	v_cmp_ngt_f32_e32 vcc, s44, v78
	s_or_b64 s[6:7], s[6:7], vcc
	v_cmp_ngt_f32_e32 vcc, s44, v79
	s_or_b64 s[6:7], s[6:7], vcc
	v_cndmask_b32_e64 v80, 0, 1, s[6:7]
	v_cmp_ne_u32_e32 vcc, 0, v80
	s_cmp_lg_u64 vcc, 0
	s_cselect_b64 s[6:7], -1, 0
	v_cndmask_b32_e64 v80, 0, 1, s[6:7]
	v_readlane_b32 s6, v246, 17
	s_nop 1
	v_mov_b32_e32 v81, s6
	ds_write_b32 v81, v80
